# A/B: inverted K-loop priorities (load segments prio 1, MFMA segments prio 0), on top of combined edits
# baseline (speedup 1.0000x reference)
; #define PG8_STAGE(bufoff, gbase, voff) do { _Pragma("unroll") for (int _i = 0; _i < 2; ++_i) \
;         __builtin_amdgcn_global_load_lds((const unsigned*)((const char*)(gbase) + (voff)[_i]), (LAS unsigned*)(lds + (bufoff) + ldsw + _i * 8192), 16, 0, 0); } while (0)
; #define PG8_LDA(dst, b, h) do { _Pragma("unroll") for (int m = 0; m < 4; ++m) _Pragma("unroll") for (int k = 0; k < 2; ++k) dst[m][k] = *(const LAS f16x8*)(lds + PG8_SA(b, h) + aoff + m * 2048 + k * 1024); } while (0)
; #define PG8_LDB(dst, b, h) do { _Pragma("unroll") for (int n = 0; n < 2; ++n) _Pragma("unroll") for (int k = 0; k < 2; ++k) dst[n][k] = *(const LAS f16x8*)(lds + PG8_SB(b, h) + boff + n * 2048 + k * 1024); } while (0)
; #define PG8_MMA(ai, bj, At, Bt) do { __builtin_amdgcn_s_setprio(1); _Pragma("unroll") for (int m = 0; m < 4; ++m) _Pragma("unroll") for (int n = 0; n < 2; ++n) _Pragma("unroll") for (int k = 0; k < 2; ++k) \
;         acc[ai][bj][m][n] = __builtin_amdgcn_mfma_f32_16x16x32_f16(Bt[n][k], At[m][k], acc[ai][bj][m][n], 0, 0, 0); __builtin_amdgcn_s_setprio(0); } while (0)
; #define PG8_WAIT_L(n) asm volatile("s_waitcnt lgkmcnt(" #n ")" ::: "memory")
; #define PG8_BAR __builtin_amdgcn_s_barrier()
; #define PG8_SCHED __builtin_amdgcn_sched_barrier(0)
; template <class Epi>
; __device__ __forceinline__ void gemm_phase(LAS unsigned char* lds, const Gemm g0, const StaticOrder& S, const Epi& E) {
;     ...
;             PG8_LDB(B0, 0, 0); PG8_SCHED; PG8_LDA(At, 0, 0); PG8_STAGE(PG8_SA(1, 1), a1 + hstep, voffA);
;             PG8_WAIT_L(8); PG8_BAR; PG8_WAIT_L(0); PG8_MMA(0, 0, At, B0); PG8_BAR; PG8_SCHED;
;             PG8_LDB(B1, 0, 1); PG8_STAGE(PG8_SB(0, 0), b2, voffB);
;             PG8_BAR; PG8_WAIT_L(0); PG8_MMA(0, 1, At, B1); PG8_BAR;
;             PG8_LDA(At, 0, 1); PG8_STAGE(PG8_SA(0, 0), a2, voffA);
;             PG8_BAR; PG8_WAIT_L(0); PG8_MMA(1, 0, At, B0); PG8_BAR; PG8_SCHED;
.LBB0_198:
	s_add_u32 s52, s0, 0xfff80080
	s_addc_u32 s53, s1, -1
	s_and_b64 s[22:23], s[50:51], exec
	s_cselect_b32 s53, s75, s53
	s_cselect_b32 s52, s80, s52
	s_add_i32 s84, 0, 0x10000
	v_add_u32_e32 v148, s84, v214
	ds_read_b128 v[136:139], v148
	ds_read_b128 v[140:143], v148 offset:1024
	ds_read_b128 v[144:147], v148 offset:2048
	ds_read_b128 v[148:151], v148 offset:3072
	s_and_b64 s[22:23], s[50:51], exec
	s_cselect_b32 s51, s81, s25
	s_cselect_b32 s50, s82, s24
	v_lshl_add_u64 v[160:161], s[0:1], 0, v[184:185]
	s_add_i32 m0, s28, 0xc000
	ds_read_b128 v[152:155], v222
	ds_read_b128 v[156:159], v222 offset:1024
	ds_read_b128 v[186:189], v222 offset:2048
	ds_read_b128 v[190:193], v222 offset:3072
	ds_read_b128 v[194:197], v222 offset:4096
	ds_read_b128 v[198:201], v222 offset:5120
	ds_read_b128 v[202:205], v222 offset:6144
	ds_read_b128 v[206:209], v222 offset:7168
	global_load_lds_dwordx4 v[160:161], off
	v_lshl_add_u64 v[160:161], s[0:1], 0, v[182:183]
	s_add_i32 m0, s28, 0xe000
	s_nop 0
	global_load_lds_dwordx4 v[160:161], off
	s_waitcnt lgkmcnt(8)
	s_barrier
	s_waitcnt lgkmcnt(0)
	s_setprio 0
	s_waitcnt lgkmcnt(0)
	v_mfma_f32_16x16x32_f16 v[126:129], v[136:139], v[152:155], v[126:129]
	v_mfma_f32_16x16x32_f16 v[122:125], v[144:147], v[152:155], v[122:125]
	v_mfma_f32_16x16x32_f16 v[118:121], v[136:139], v[186:189], v[118:121]
	v_mfma_f32_16x16x32_f16 v[110:113], v[144:147], v[186:189], v[110:113]
	v_mfma_f32_16x16x32_f16 v[102:105], v[136:139], v[194:197], v[102:105]
	v_mfma_f32_16x16x32_f16 v[98:101], v[144:147], v[194:197], v[98:101]
	v_mfma_f32_16x16x32_f16 v[86:89], v[136:139], v[202:205], v[86:89]
	v_mfma_f32_16x16x32_f16 v[82:85], v[144:147], v[202:205], v[82:85]
	v_mfma_f32_16x16x32_f16 v[126:129], v[140:143], v[156:159], v[126:129]
	v_mfma_f32_16x16x32_f16 v[122:125], v[148:151], v[156:159], v[122:125]
	v_mfma_f32_16x16x32_f16 v[118:121], v[140:143], v[190:193], v[118:121]
	v_mfma_f32_16x16x32_f16 v[110:113], v[148:151], v[190:193], v[110:113]
	v_mfma_f32_16x16x32_f16 v[102:105], v[140:143], v[198:201], v[102:105]
	v_mfma_f32_16x16x32_f16 v[98:101], v[148:151], v[198:201], v[98:101]
	v_mfma_f32_16x16x32_f16 v[86:89], v[140:143], v[206:209], v[86:89]
	v_mfma_f32_16x16x32_f16 v[82:85], v[148:151], v[206:209], v[82:85]
	s_setprio 1
	s_barrier
	s_add_i32 s85, 0, 0x14000
	v_add_u32_e32 v160, s85, v214
	s_add_i32 s22, s84, s19
	ds_read_b128 v[210:213], v160
	ds_read_b128 v[234:237], v160 offset:1024
	ds_read_b128 v[238:241], v160 offset:2048
	ds_read_b128 v[242:245], v160 offset:3072
	v_lshl_add_u64 v[160:161], s[50:51], 0, v[178:179]
	s_mov_b32 m0, s22
	v_lshl_add_u64 v[162:163], s[50:51], 0, v[174:175]
	global_load_lds_dwordx4 v[160:161], off
	s_add_i32 m0, s22, 0x2000
	s_nop 0
	global_load_lds_dwordx4 v[162:163], off
	s_barrier
	s_waitcnt lgkmcnt(0)
	s_setprio 0
	s_waitcnt lgkmcnt(0)
	v_mfma_f32_16x16x32_f16 v[114:117], v[210:213], v[152:155], v[114:117]
	v_mfma_f32_16x16x32_f16 v[106:109], v[238:241], v[152:155], v[106:109]
	v_mfma_f32_16x16x32_f16 v[94:97], v[210:213], v[186:189], v[94:97]
	v_mfma_f32_16x16x32_f16 v[90:93], v[238:241], v[186:189], v[90:93]
	v_mfma_f32_16x16x32_f16 v[78:81], v[210:213], v[194:197], v[78:81]
	v_mfma_f32_16x16x32_f16 v[74:77], v[238:241], v[194:197], v[74:77]
	v_mfma_f32_16x16x32_f16 v[70:73], v[210:213], v[202:205], v[70:73]
	v_mfma_f32_16x16x32_f16 v[66:69], v[238:241], v[202:205], v[66:69]
	v_mfma_f32_16x16x32_f16 v[114:117], v[234:237], v[156:159], v[114:117]
	v_mfma_f32_16x16x32_f16 v[106:109], v[242:245], v[156:159], v[106:109]
	v_mfma_f32_16x16x32_f16 v[94:97], v[234:237], v[190:193], v[94:97]
	v_mfma_f32_16x16x32_f16 v[90:93], v[242:245], v[190:193], v[90:93]
	v_mfma_f32_16x16x32_f16 v[78:81], v[234:237], v[198:201], v[78:81]
	v_mfma_f32_16x16x32_f16 v[74:77], v[242:245], v[198:201], v[74:77]
	v_mfma_f32_16x16x32_f16 v[70:73], v[234:237], v[206:209], v[70:73]
	v_mfma_f32_16x16x32_f16 v[66:69], v[242:245], v[206:209], v[66:69]
	s_setprio 1
	s_mov_b32 m0, s28
	v_lshl_add_u64 v[164:165], s[52:53], 0, v[180:181]
	s_barrier
	ds_read_b128 v[152:155], v222 offset:16384
	ds_read_b128 v[156:159], v222 offset:17408
	ds_read_b128 v[186:189], v222 offset:18432
	ds_read_b128 v[190:193], v222 offset:19456
	ds_read_b128 v[194:197], v222 offset:20480
	ds_read_b128 v[198:201], v222 offset:21504
	ds_read_b128 v[202:205], v222 offset:22528
	ds_read_b128 v[206:209], v222 offset:23552
	global_load_lds_dwordx4 v[164:165], off
	v_lshl_add_u64 v[170:171], s[52:53], 0, v[176:177]
	s_mov_b32 m0, s29
	s_nop 0
	global_load_lds_dwordx4 v[170:171], off
	s_barrier
	s_waitcnt lgkmcnt(0)
	s_setprio 0
	s_waitcnt lgkmcnt(0)
	v_mfma_f32_16x16x32_f16 v[62:65], v[136:139], v[152:155], v[62:65]
	v_mfma_f32_16x16x32_f16 v[58:61], v[144:147], v[152:155], v[58:61]
	v_mfma_f32_16x16x32_f16 v[54:57], v[136:139], v[186:189], v[54:57]
	v_mfma_f32_16x16x32_f16 v[50:53], v[144:147], v[186:189], v[50:53]
	v_mfma_f32_16x16x32_f16 v[38:41], v[136:139], v[194:197], v[38:41]
	v_mfma_f32_16x16x32_f16 v[30:33], v[144:147], v[194:197], v[30:33]
	v_mfma_f32_16x16x32_f16 v[22:25], v[136:139], v[202:205], v[22:25]
	v_mfma_f32_16x16x32_f16 v[18:21], v[144:147], v[202:205], v[18:21]
	v_mfma_f32_16x16x32_f16 v[62:65], v[140:143], v[156:159], v[62:65]
	v_mfma_f32_16x16x32_f16 v[58:61], v[148:151], v[156:159], v[58:61]
	v_mfma_f32_16x16x32_f16 v[54:57], v[140:143], v[190:193], v[54:57]
	v_mfma_f32_16x16x32_f16 v[50:53], v[148:151], v[190:193], v[50:53]
	v_mfma_f32_16x16x32_f16 v[38:41], v[140:143], v[198:201], v[38:41]
	v_mfma_f32_16x16x32_f16 v[30:33], v[148:151], v[198:201], v[30:33]
	v_mfma_f32_16x16x32_f16 v[22:25], v[140:143], v[206:209], v[22:25]
	v_mfma_f32_16x16x32_f16 v[18:21], v[148:151], v[206:209], v[18:21]
	s_setprio 1
	s_barrier
; #define PG8_STAGE(bufoff, gbase, voff) do { _Pragma("unroll") for (int _i = 0; _i < 2; ++_i) \
;         __builtin_amdgcn_global_load_lds((const unsigned*)((const char*)(gbase) + (voff)[_i]), (LAS unsigned*)(lds + (bufoff) + ldsw + _i * 8192), 16, 0, 0); } while (0)
; #define PG8_LDA(dst, b, h) do { _Pragma("unroll") for (int m = 0; m < 4; ++m) _Pragma("unroll") for (int k = 0; k < 2; ++k) dst[m][k] = *(const LAS f16x8*)(lds + PG8_SA(b, h) + aoff + m * 2048 + k * 1024); } while (0)
; #define PG8_LDB(dst, b, h) do { _Pragma("unroll") for (int n = 0; n < 2; ++n) _Pragma("unroll") for (int k = 0; k < 2; ++k) dst[n][k] = *(const LAS f16x8*)(lds + PG8_SB(b, h) + boff + n * 2048 + k * 1024); } while (0)
; #define PG8_MMA(ai, bj, At, Bt) do { __builtin_amdgcn_s_setprio(1); _Pragma("unroll") for (int m = 0; m < 4; ++m) _Pragma("unroll") for (int n = 0; n < 2; ++n) _Pragma("unroll") for (int k = 0; k < 2; ++k) \
;         acc[ai][bj][m][n] = __builtin_amdgcn_mfma_f32_16x16x32_f16(Bt[n][k], At[m][k], acc[ai][bj][m][n], 0, 0, 0); __builtin_amdgcn_s_setprio(0); } while (0)
; #define PG8_WAIT_V(n) asm volatile("s_waitcnt vmcnt(" #n ")" ::: "memory")
; #define PG8_WAIT_L(n) asm volatile("s_waitcnt lgkmcnt(" #n ")" ::: "memory")
; #define PG8_BAR __builtin_amdgcn_s_barrier()
; #define PG8_SCHED __builtin_amdgcn_sched_barrier(0)
; template <class Epi>
; __device__ __forceinline__ void gemm_phase(LAS unsigned char* lds, const Gemm g0, const StaticOrder& S, const Epi& E) {
;     ...
;             PG8_STAGE(PG8_SB(0, 1), b2 + hstep, voffB);
;             PG8_WAIT_V(6); PG8_BAR; PG8_MMA(1, 1, At, B1); PG8_BAR;
;             PG8_LDB(B0, 1, 0); PG8_SCHED; PG8_LDA(At, 1, 0); PG8_STAGE(PG8_SA(0, 1), a2 + hstep, voffA);
;             PG8_WAIT_L(8); PG8_BAR; PG8_WAIT_L(0); PG8_MMA(0, 0, At, B0); PG8_BAR; PG8_SCHED;
	s_add_u32 s22, s50, 0x80000
	s_addc_u32 s23, s51, 0
	s_add_i32 s84, s85, s19
	v_lshl_add_u64 v[136:137], s[22:23], 0, v[178:179]
	s_mov_b32 m0, s84
	s_nop 0
	global_load_lds_dwordx4 v[136:137], off
	v_lshl_add_u64 v[136:137], s[22:23], 0, v[174:175]
	s_add_i32 m0, s84, 0x2000
	s_nop 0
	global_load_lds_dwordx4 v[136:137], off
	s_waitcnt vmcnt(6)
	s_barrier
	s_setprio 0
	v_mfma_f32_16x16x32_f16 v[46:49], v[210:213], v[152:155], v[46:49]
	v_mfma_f32_16x16x32_f16 v[42:45], v[238:241], v[152:155], v[42:45]
	v_mfma_f32_16x16x32_f16 v[34:37], v[210:213], v[186:189], v[34:37]
	v_mfma_f32_16x16x32_f16 v[26:29], v[238:241], v[186:189], v[26:29]
	v_mfma_f32_16x16x32_f16 v[14:17], v[210:213], v[194:197], v[14:17]
	v_mfma_f32_16x16x32_f16 v[10:13], v[238:241], v[194:197], v[10:13]
	v_mfma_f32_16x16x32_f16 v[6:9], v[210:213], v[202:205], v[6:9]
	v_mfma_f32_16x16x32_f16 v[2:5], v[238:241], v[202:205], v[2:5]
	v_mfma_f32_16x16x32_f16 v[46:49], v[234:237], v[156:159], v[46:49]
	v_mfma_f32_16x16x32_f16 v[42:45], v[242:245], v[156:159], v[42:45]
	v_mfma_f32_16x16x32_f16 v[34:37], v[234:237], v[190:193], v[34:37]
	v_mfma_f32_16x16x32_f16 v[26:29], v[242:245], v[190:193], v[26:29]
	v_mfma_f32_16x16x32_f16 v[14:17], v[234:237], v[198:201], v[14:17]
	v_mfma_f32_16x16x32_f16 v[10:13], v[242:245], v[198:201], v[10:13]
	v_mfma_f32_16x16x32_f16 v[6:9], v[234:237], v[206:209], v[6:9]
	v_mfma_f32_16x16x32_f16 v[2:5], v[242:245], v[206:209], v[2:5]
	s_setprio 1
	s_add_i32 s84, 0, 0x18000
	v_add_u32_e32 v148, s84, v214
	s_barrier
	ds_read_b128 v[136:139], v148
	ds_read_b128 v[140:143], v148 offset:1024
	ds_read_b128 v[144:147], v148 offset:2048
	ds_read_b128 v[148:151], v148 offset:3072
	s_add_u32 s22, s52, 0x80000
	s_addc_u32 s23, s53, 0
	s_mov_b32 m0, s31
	v_lshl_add_u64 v[172:173], s[22:23], 0, v[180:181]
	ds_read_b128 v[152:155], v222 offset:32768
	ds_read_b128 v[156:159], v222 offset:33792
	ds_read_b128 v[186:189], v222 offset:34816
	ds_read_b128 v[190:193], v222 offset:35840
	ds_read_b128 v[194:197], v222 offset:36864
	ds_read_b128 v[198:201], v222 offset:37888
	ds_read_b128 v[202:205], v222 offset:38912
	ds_read_b128 v[206:209], v222 offset:39936
	global_load_lds_dwordx4 v[172:173], off
	v_lshl_add_u64 v[172:173], s[22:23], 0, v[176:177]
	s_mov_b32 m0, s58
	s_nop 0
	global_load_lds_dwordx4 v[172:173], off
	s_waitcnt lgkmcnt(8)
	s_barrier
	s_waitcnt lgkmcnt(0)
	s_setprio 0
	s_waitcnt lgkmcnt(0)
	v_mfma_f32_16x16x32_f16 v[126:129], v[136:139], v[152:155], v[126:129]
	v_mfma_f32_16x16x32_f16 v[122:125], v[144:147], v[152:155], v[122:125]
	v_mfma_f32_16x16x32_f16 v[118:121], v[136:139], v[186:189], v[118:121]
	v_mfma_f32_16x16x32_f16 v[110:113], v[144:147], v[186:189], v[110:113]
	v_mfma_f32_16x16x32_f16 v[102:105], v[136:139], v[194:197], v[102:105]
	v_mfma_f32_16x16x32_f16 v[98:101], v[144:147], v[194:197], v[98:101]
	v_mfma_f32_16x16x32_f16 v[86:89], v[136:139], v[202:205], v[86:89]
	v_mfma_f32_16x16x32_f16 v[82:85], v[144:147], v[202:205], v[82:85]
	v_mfma_f32_16x16x32_f16 v[126:129], v[140:143], v[156:159], v[126:129]
	v_mfma_f32_16x16x32_f16 v[122:125], v[148:151], v[156:159], v[122:125]
	v_mfma_f32_16x16x32_f16 v[118:121], v[140:143], v[190:193], v[118:121]
	v_mfma_f32_16x16x32_f16 v[110:113], v[148:151], v[190:193], v[110:113]
	v_mfma_f32_16x16x32_f16 v[102:105], v[140:143], v[198:201], v[102:105]
	v_mfma_f32_16x16x32_f16 v[98:101], v[148:151], v[198:201], v[98:101]
	v_mfma_f32_16x16x32_f16 v[86:89], v[140:143], v[206:209], v[86:89]
	v_mfma_f32_16x16x32_f16 v[82:85], v[148:151], v[206:209], v[82:85]
	s_setprio 1
	s_barrier
	s_add_i32 s52, 0, 0x1c000
	s_add_i32 s22, s84, s19
	v_add_u32_e32 v172, s52, v214
	v_lshl_add_u64 v[160:161], v[160:161], 0, s[64:65]
	s_mov_b32 m0, s22
	ds_read_b128 v[210:213], v172
	ds_read_b128 v[234:237], v172 offset:1024
	ds_read_b128 v[238:241], v172 offset:2048
	ds_read_b128 v[242:245], v172 offset:3072
	global_load_lds_dwordx4 v[160:161], off
	v_lshl_add_u64 v[160:161], v[162:163], 0, s[64:65]
	s_add_i32 m0, s22, 0x2000
	s_nop 0
	global_load_lds_dwordx4 v[160:161], off
	s_barrier
; #define PG8_STAGE(bufoff, gbase, voff) do { _Pragma("unroll") for (int _i = 0; _i < 2; ++_i) \
;         __builtin_amdgcn_global_load_lds((const unsigned*)((const char*)(gbase) + (voff)[_i]), (LAS unsigned*)(lds + (bufoff) + ldsw + _i * 8192), 16, 0, 0); } while (0)
; #define PG8_LDA(dst, b, h) do { _Pragma("unroll") for (int m = 0; m < 4; ++m) _Pragma("unroll") for (int k = 0; k < 2; ++k) dst[m][k] = *(const LAS f16x8*)(lds + PG8_SA(b, h) + aoff + m * 2048 + k * 1024); } while (0)
; #define PG8_LDB(dst, b, h) do { _Pragma("unroll") for (int n = 0; n < 2; ++n) _Pragma("unroll") for (int k = 0; k < 2; ++k) dst[n][k] = *(const LAS f16x8*)(lds + PG8_SB(b, h) + boff + n * 2048 + k * 1024); } while (0)
; #define PG8_MMA(ai, bj, At, Bt) do { __builtin_amdgcn_s_setprio(1); _Pragma("unroll") for (int m = 0; m < 4; ++m) _Pragma("unroll") for (int n = 0; n < 2; ++n) _Pragma("unroll") for (int k = 0; k < 2; ++k) \
;         acc[ai][bj][m][n] = __builtin_amdgcn_mfma_f32_16x16x32_f16(Bt[n][k], At[m][k], acc[ai][bj][m][n], 0, 0, 0); __builtin_amdgcn_s_setprio(0); } while (0)
; #define PG8_WAIT_V(n) asm volatile("s_waitcnt vmcnt(" #n ")" ::: "memory")
; #define PG8_WAIT_L(n) asm volatile("s_waitcnt lgkmcnt(" #n ")" ::: "memory")
; #define PG8_BAR __builtin_amdgcn_s_barrier()
; #define PG8_SCHED __builtin_amdgcn_sched_barrier(0)
; template <class Epi>
; __device__ __forceinline__ void gemm_phase(LAS unsigned char* lds, const Gemm g0, const StaticOrder& S, const Epi& E) {
;     ...
;             PG8_LDB(B1, 1, 1); PG8_STAGE(PG8_SB(1, 0), b3, voffB);
;             PG8_BAR; PG8_WAIT_L(0); PG8_MMA(0, 1, At, B1); PG8_BAR;
;             PG8_LDA(At, 1, 1); PG8_STAGE(PG8_SA(1, 0), a3, voffA);
;             PG8_BAR; PG8_WAIT_L(0); PG8_MMA(1, 0, At, B0); PG8_BAR; PG8_SCHED;
;             PG8_STAGE(PG8_SB(1, 1), b3 + hstep, voffB);
;             PG8_WAIT_V(6); PG8_BAR; PG8_MMA(1, 1, At, B1); PG8_BAR;
	s_waitcnt lgkmcnt(0)
	s_setprio 0
	s_waitcnt lgkmcnt(0)
	v_mfma_f32_16x16x32_f16 v[114:117], v[210:213], v[152:155], v[114:117]
	v_mfma_f32_16x16x32_f16 v[106:109], v[238:241], v[152:155], v[106:109]
	v_mfma_f32_16x16x32_f16 v[94:97], v[210:213], v[186:189], v[94:97]
	v_mfma_f32_16x16x32_f16 v[90:93], v[238:241], v[186:189], v[90:93]
	v_mfma_f32_16x16x32_f16 v[78:81], v[210:213], v[194:197], v[78:81]
	v_mfma_f32_16x16x32_f16 v[74:77], v[238:241], v[194:197], v[74:77]
	v_mfma_f32_16x16x32_f16 v[70:73], v[210:213], v[202:205], v[70:73]
	v_mfma_f32_16x16x32_f16 v[66:69], v[238:241], v[202:205], v[66:69]
	v_mfma_f32_16x16x32_f16 v[114:117], v[234:237], v[156:159], v[114:117]
	v_mfma_f32_16x16x32_f16 v[106:109], v[242:245], v[156:159], v[106:109]
	v_mfma_f32_16x16x32_f16 v[94:97], v[234:237], v[190:193], v[94:97]
	v_mfma_f32_16x16x32_f16 v[90:93], v[242:245], v[190:193], v[90:93]
	v_mfma_f32_16x16x32_f16 v[78:81], v[234:237], v[198:201], v[78:81]
	v_mfma_f32_16x16x32_f16 v[74:77], v[242:245], v[198:201], v[74:77]
	v_mfma_f32_16x16x32_f16 v[70:73], v[234:237], v[206:209], v[70:73]
	v_mfma_f32_16x16x32_f16 v[66:69], v[242:245], v[206:209], v[66:69]
	s_setprio 1
	s_mov_b32 m0, s59
	v_lshl_add_u64 v[160:161], v[164:165], 0, s[64:65]
	s_barrier
	ds_read_b128 v[152:155], v222 offset:49152
	ds_read_b128 v[156:159], v222 offset:50176
	ds_read_b128 v[186:189], v222 offset:51200
	ds_read_b128 v[190:193], v222 offset:52224
	ds_read_b128 v[194:197], v222 offset:53248
	ds_read_b128 v[198:201], v222 offset:54272
	ds_read_b128 v[202:205], v222 offset:55296
	ds_read_b128 v[206:209], v222 offset:56320
	global_load_lds_dwordx4 v[160:161], off
	v_lshl_add_u64 v[160:161], v[170:171], 0, s[64:65]
	s_mov_b32 m0, s61
	s_nop 0
	global_load_lds_dwordx4 v[160:161], off
	s_barrier
	s_waitcnt lgkmcnt(0)
	s_setprio 0
	s_waitcnt lgkmcnt(0)
	v_mfma_f32_16x16x32_f16 v[62:65], v[136:139], v[152:155], v[62:65]
	v_mfma_f32_16x16x32_f16 v[58:61], v[144:147], v[152:155], v[58:61]
	v_mfma_f32_16x16x32_f16 v[54:57], v[136:139], v[186:189], v[54:57]
	v_mfma_f32_16x16x32_f16 v[50:53], v[144:147], v[186:189], v[50:53]
	v_mfma_f32_16x16x32_f16 v[38:41], v[136:139], v[194:197], v[38:41]
	v_mfma_f32_16x16x32_f16 v[30:33], v[144:147], v[194:197], v[30:33]
	v_mfma_f32_16x16x32_f16 v[22:25], v[136:139], v[202:205], v[22:25]
	v_mfma_f32_16x16x32_f16 v[18:21], v[144:147], v[202:205], v[18:21]
	v_mfma_f32_16x16x32_f16 v[62:65], v[140:143], v[156:159], v[62:65]
	v_mfma_f32_16x16x32_f16 v[58:61], v[148:151], v[156:159], v[58:61]
	v_mfma_f32_16x16x32_f16 v[54:57], v[140:143], v[190:193], v[54:57]
	v_mfma_f32_16x16x32_f16 v[50:53], v[148:151], v[190:193], v[50:53]
	v_mfma_f32_16x16x32_f16 v[38:41], v[140:143], v[198:201], v[38:41]
	v_mfma_f32_16x16x32_f16 v[30:33], v[148:151], v[198:201], v[30:33]
	v_mfma_f32_16x16x32_f16 v[22:25], v[140:143], v[206:209], v[22:25]
	v_mfma_f32_16x16x32_f16 v[18:21], v[148:151], v[206:209], v[18:21]
	s_setprio 1
	s_barrier
	s_add_u32 s22, s50, 0x80080
	s_addc_u32 s23, s51, 0
	s_add_i32 s50, s52, s19
	v_lshl_add_u64 v[136:137], s[22:23], 0, v[178:179]
	s_mov_b32 m0, s50
	s_nop 0
	global_load_lds_dwordx4 v[136:137], off
	v_lshl_add_u64 v[136:137], s[22:23], 0, v[174:175]
	s_add_i32 m0, s50, 0x2000
	s_nop 0
	global_load_lds_dwordx4 v[136:137], off
	s_waitcnt vmcnt(6)
	s_barrier
	s_setprio 0
	v_mfma_f32_16x16x32_f16 v[46:49], v[210:213], v[152:155], v[46:49]
	v_mfma_f32_16x16x32_f16 v[42:45], v[238:241], v[152:155], v[42:45]
	v_mfma_f32_16x16x32_f16 v[34:37], v[210:213], v[186:189], v[34:37]
	v_mfma_f32_16x16x32_f16 v[26:29], v[238:241], v[186:189], v[26:29]
	v_mfma_f32_16x16x32_f16 v[14:17], v[210:213], v[194:197], v[14:17]
	v_mfma_f32_16x16x32_f16 v[10:13], v[238:241], v[194:197], v[10:13]
	v_mfma_f32_16x16x32_f16 v[6:9], v[210:213], v[202:205], v[6:9]
	v_mfma_f32_16x16x32_f16 v[2:5], v[238:241], v[202:205], v[2:5]
	v_mfma_f32_16x16x32_f16 v[46:49], v[234:237], v[156:159], v[46:49]
	v_mfma_f32_16x16x32_f16 v[42:45], v[242:245], v[156:159], v[42:45]
	v_mfma_f32_16x16x32_f16 v[34:37], v[234:237], v[190:193], v[34:37]
	v_mfma_f32_16x16x32_f16 v[26:29], v[242:245], v[190:193], v[26:29]
	v_mfma_f32_16x16x32_f16 v[14:17], v[234:237], v[198:201], v[14:17]
	v_mfma_f32_16x16x32_f16 v[10:13], v[242:245], v[198:201], v[10:13]
	v_mfma_f32_16x16x32_f16 v[6:9], v[234:237], v[206:209], v[6:9]
	v_mfma_f32_16x16x32_f16 v[2:5], v[242:245], v[206:209], v[2:5]
	s_setprio 1
	s_add_i32 s83, s83, 2
	s_add_u32 s24, s24, 0x100
	s_addc_u32 s25, s25, 0
	s_add_u32 s0, s0, 0x100
	s_addc_u32 s1, s1, 0
	s_cmp_gt_u32 s83, 29
	s_barrier
	s_cbranch_scc1 .LBB0_201

;     __device__ __forceinline__ void prefetch(const Unit& u, int wr, int wc, int lane) const { lnfold_prefetch(vl, stats, gW, bW, u, wr, wc, lane); }
;     __device__ __forceinline__ void prefetch(const Unit& u, int wr, int wc, int lane) const { lnfold_prefetch(vl, stats, gW, bW, u, wr, wc, lane); }
; #define PG8_STAGE(bufoff, gbase, voff) do { _Pragma("unroll") for (int _i = 0; _i < 2; ++_i) \
;         __builtin_amdgcn_global_load_lds((const unsigned*)((const char*)(gbase) + (voff)[_i]), (LAS unsigned*)(lds + (bufoff) + ldsw + _i * 8192), 16, 0, 0); } while (0)
; #define PG8_LDA(dst, b, h) do { _Pragma("unroll") for (int m = 0; m < 4; ++m) _Pragma("unroll") for (int k = 0; k < 2; ++k) dst[m][k] = *(const LAS f16x8*)(lds + PG8_SA(b, h) + aoff + m * 2048 + k * 1024); } while (0)
; #define PG8_LDB(dst, b, h) do { _Pragma("unroll") for (int n = 0; n < 2; ++n) _Pragma("unroll") for (int k = 0; k < 2; ++k) dst[n][k] = *(const LAS f16x8*)(lds + PG8_SB(b, h) + boff + n * 2048 + k * 1024); } while (0)
; #define PG8_MMA(ai, bj, At, Bt) do { __builtin_amdgcn_s_setprio(1); _Pragma("unroll") for (int m = 0; m < 4; ++m) _Pragma("unroll") for (int n = 0; n < 2; ++n) _Pragma("unroll") for (int k = 0; k < 2; ++k) \
;         acc[ai][bj][m][n] = __builtin_amdgcn_mfma_f32_16x16x32_f16(Bt[n][k], At[m][k], acc[ai][bj][m][n], 0, 0, 0); __builtin_amdgcn_s_setprio(0); } while (0)
; template <class Epi>
; __device__ __forceinline__ void gemm_phase(LAS unsigned char* lds, const Gemm g0, const StaticOrder& S, const Epi& E) {
;     ...
;             const bool last = (t == nt - 2);
;             if (Epi::PREF && last) E.prefetch(cur, wr, wc, lane);
;             const char* a1 = cA + (size_t)(t + 1) * kstep;
;             const char* a2 = last ? nA : cA + (size_t)(t + 2) * kstep; const char* b2 = last ? nB : cB + (size_t)(t + 2) * kstep;
;             const char* a3 = a2 + kstep; const char* b3 = b2 + kstep;
;             PG8_LDB(B0, 0, 0); PG8_SCHED; PG8_LDA(At, 0, 0); PG8_STAGE(PG8_SA(1, 1), a1 + hstep, voffA);
;             PG8_WAIT_L(8); PG8_BAR; PG8_WAIT_L(0); PG8_MMA(0, 0, At, B0); PG8_BAR; PG8_SCHED;
;             PG8_LDB(B1, 0, 1); PG8_STAGE(PG8_SB(0, 0), b2, voffB);
;             PG8_BAR; PG8_WAIT_L(0); PG8_MMA(0, 1, At, B1); PG8_BAR;
;             PG8_LDA(At, 0, 1); PG8_STAGE(PG8_SA(0, 0), a2, voffA);
;             PG8_BAR; PG8_WAIT_L(0); PG8_MMA(1, 0, At, B0); PG8_BAR; PG8_SCHED;
.LBB0_302:
	s_add_u32 s22, s6, 0xfff80080
	s_addc_u32 s23, s7, -1
	s_add_i32 s59, 0, 0x10000
	v_add_u32_e32 v146, s59, v148
	ds_read_b128 v[142:145], v146
	ds_read_b128 v[152:155], v146 offset:1024
	ds_read_b128 v[156:159], v146 offset:2048
	ds_read_b128 v[174:177], v146 offset:3072
	s_cmp_eq_u32 s58, 28
	s_cselect_b32 s37, s15, s23
	s_cselect_b32 s36, s52, s22
	s_cselect_b32 s35, s13, s53
	s_cselect_b32 s34, s24, s25
	v_lshl_add_u64 v[146:147], s[6:7], 0, v[140:141]
	s_add_i32 m0, s28, 0xc000
	ds_read_b128 v[178:181], v150
	ds_read_b128 v[182:185], v150 offset:1024
	ds_read_b128 v[186:189], v150 offset:2048
	ds_read_b128 v[190:193], v150 offset:3072
	ds_read_b128 v[194:197], v150 offset:4096
	ds_read_b128 v[198:201], v150 offset:5120
	ds_read_b128 v[202:205], v150 offset:6144
	ds_read_b128 v[206:209], v150 offset:7168
	global_load_lds_dwordx4 v[146:147], off
	v_lshl_add_u64 v[146:147], s[6:7], 0, v[138:139]
	s_add_i32 m0, s28, 0xe000
	s_nop 0
	global_load_lds_dwordx4 v[146:147], off
	s_waitcnt lgkmcnt(8)
	s_barrier
	s_waitcnt lgkmcnt(0)
	s_setprio 0
	s_waitcnt lgkmcnt(0)
	v_mfma_f32_16x16x32_f16 v[126:129], v[142:145], v[178:181], v[126:129]
	v_mfma_f32_16x16x32_f16 v[122:125], v[156:159], v[178:181], v[122:125]
	v_mfma_f32_16x16x32_f16 v[110:113], v[142:145], v[186:189], v[110:113]
	v_mfma_f32_16x16x32_f16 v[106:109], v[156:159], v[186:189], v[106:109]
	v_mfma_f32_16x16x32_f16 v[94:97], v[142:145], v[194:197], v[94:97]
	v_mfma_f32_16x16x32_f16 v[90:93], v[156:159], v[194:197], v[90:93]
	v_mfma_f32_16x16x32_f16 v[78:81], v[142:145], v[202:205], v[78:81]
	v_mfma_f32_16x16x32_f16 v[74:77], v[156:159], v[202:205], v[74:77]
	v_mfma_f32_16x16x32_f16 v[126:129], v[152:155], v[182:185], v[126:129]
	v_mfma_f32_16x16x32_f16 v[122:125], v[174:177], v[182:185], v[122:125]
	v_mfma_f32_16x16x32_f16 v[110:113], v[152:155], v[190:193], v[110:113]
	v_mfma_f32_16x16x32_f16 v[106:109], v[174:177], v[190:193], v[106:109]
	v_mfma_f32_16x16x32_f16 v[94:97], v[152:155], v[198:201], v[94:97]
	v_mfma_f32_16x16x32_f16 v[90:93], v[174:177], v[198:201], v[90:93]
	v_mfma_f32_16x16x32_f16 v[78:81], v[152:155], v[206:209], v[78:81]
	v_mfma_f32_16x16x32_f16 v[74:77], v[174:177], v[206:209], v[74:77]
	s_setprio 1
	s_barrier
	s_add_i32 s61, 0, 0x14000
	v_add_u32_e32 v146, s61, v148
	s_add_i32 s22, s59, s19
	ds_read_b128 v[210:213], v146
	ds_read_b128 v[234:237], v146 offset:1024
	ds_read_b128 v[238:241], v146 offset:2048
	ds_read_b128 v[242:245], v146 offset:3072
	v_lshl_add_u64 v[146:147], s[34:35], 0, v[134:135]
	s_mov_b32 m0, s22
	v_lshl_add_u64 v[160:161], s[34:35], 0, v[130:131]
	global_load_lds_dwordx4 v[146:147], off
	s_add_i32 m0, s22, 0x2000
	s_nop 0
	global_load_lds_dwordx4 v[160:161], off
	s_barrier
	s_waitcnt lgkmcnt(0)
	s_setprio 0
	s_waitcnt lgkmcnt(0)
	v_mfma_f32_16x16x32_f16 v[118:121], v[210:213], v[178:181], v[118:121]
	v_mfma_f32_16x16x32_f16 v[114:117], v[238:241], v[178:181], v[114:117]
	v_mfma_f32_16x16x32_f16 v[102:105], v[210:213], v[186:189], v[102:105]
	v_mfma_f32_16x16x32_f16 v[98:101], v[238:241], v[186:189], v[98:101]
	v_mfma_f32_16x16x32_f16 v[86:89], v[210:213], v[194:197], v[86:89]
	v_mfma_f32_16x16x32_f16 v[82:85], v[238:241], v[194:197], v[82:85]
	v_mfma_f32_16x16x32_f16 v[70:73], v[210:213], v[202:205], v[70:73]
	v_mfma_f32_16x16x32_f16 v[66:69], v[238:241], v[202:205], v[66:69]
	v_mfma_f32_16x16x32_f16 v[118:121], v[234:237], v[182:185], v[118:121]
	v_mfma_f32_16x16x32_f16 v[114:117], v[242:245], v[182:185], v[114:117]
	v_mfma_f32_16x16x32_f16 v[102:105], v[234:237], v[190:193], v[102:105]
	v_mfma_f32_16x16x32_f16 v[98:101], v[242:245], v[190:193], v[98:101]
	v_mfma_f32_16x16x32_f16 v[86:89], v[234:237], v[198:201], v[86:89]
	v_mfma_f32_16x16x32_f16 v[82:85], v[242:245], v[198:201], v[82:85]
	v_mfma_f32_16x16x32_f16 v[70:73], v[234:237], v[206:209], v[70:73]
	v_mfma_f32_16x16x32_f16 v[66:69], v[242:245], v[206:209], v[66:69]
	s_setprio 1
	s_mov_b32 m0, s28
	v_lshl_add_u64 v[162:163], s[36:37], 0, v[136:137]
	s_barrier
	ds_read_b128 v[178:181], v150 offset:16384
	ds_read_b128 v[182:185], v150 offset:17408
	ds_read_b128 v[186:189], v150 offset:18432
	ds_read_b128 v[190:193], v150 offset:19456
	ds_read_b128 v[194:197], v150 offset:20480
	ds_read_b128 v[198:201], v150 offset:21504
	ds_read_b128 v[202:205], v150 offset:22528
	ds_read_b128 v[206:209], v150 offset:23552
	global_load_lds_dwordx4 v[162:163], off
	v_lshl_add_u64 v[164:165], s[36:37], 0, v[132:133]
	s_mov_b32 m0, s29
	s_nop 0
	global_load_lds_dwordx4 v[164:165], off
	s_barrier
	s_waitcnt lgkmcnt(0)
	s_setprio 0
	s_waitcnt lgkmcnt(0)
	v_mfma_f32_16x16x32_f16 v[62:65], v[142:145], v[178:181], v[62:65]
	v_mfma_f32_16x16x32_f16 v[58:61], v[156:159], v[178:181], v[58:61]
	v_mfma_f32_16x16x32_f16 v[46:49], v[142:145], v[186:189], v[46:49]
	v_mfma_f32_16x16x32_f16 v[42:45], v[156:159], v[186:189], v[42:45]
	v_mfma_f32_16x16x32_f16 v[30:33], v[142:145], v[194:197], v[30:33]
	v_mfma_f32_16x16x32_f16 v[26:29], v[156:159], v[194:197], v[26:29]
	v_mfma_f32_16x16x32_f16 v[14:17], v[142:145], v[202:205], v[14:17]
	v_mfma_f32_16x16x32_f16 v[10:13], v[156:159], v[202:205], v[10:13]
	v_mfma_f32_16x16x32_f16 v[62:65], v[152:155], v[182:185], v[62:65]
	v_mfma_f32_16x16x32_f16 v[58:61], v[174:177], v[182:185], v[58:61]
	v_mfma_f32_16x16x32_f16 v[46:49], v[152:155], v[190:193], v[46:49]
	v_mfma_f32_16x16x32_f16 v[42:45], v[174:177], v[190:193], v[42:45]
	v_mfma_f32_16x16x32_f16 v[30:33], v[152:155], v[198:201], v[30:33]
	v_mfma_f32_16x16x32_f16 v[26:29], v[174:177], v[198:201], v[26:29]
	v_mfma_f32_16x16x32_f16 v[14:17], v[152:155], v[206:209], v[14:17]
	v_mfma_f32_16x16x32_f16 v[10:13], v[174:177], v[206:209], v[10:13]
	s_setprio 1
	s_barrier
; #define PG8_STAGE(bufoff, gbase, voff) do { _Pragma("unroll") for (int _i = 0; _i < 2; ++_i) \
;         __builtin_amdgcn_global_load_lds((const unsigned*)((const char*)(gbase) + (voff)[_i]), (LAS unsigned*)(lds + (bufoff) + ldsw + _i * 8192), 16, 0, 0); } while (0)
; #define PG8_LDA(dst, b, h) do { _Pragma("unroll") for (int m = 0; m < 4; ++m) _Pragma("unroll") for (int k = 0; k < 2; ++k) dst[m][k] = *(const LAS f16x8*)(lds + PG8_SA(b, h) + aoff + m * 2048 + k * 1024); } while (0)
; #define PG8_LDB(dst, b, h) do { _Pragma("unroll") for (int n = 0; n < 2; ++n) _Pragma("unroll") for (int k = 0; k < 2; ++k) dst[n][k] = *(const LAS f16x8*)(lds + PG8_SB(b, h) + boff + n * 2048 + k * 1024); } while (0)
; #define PG8_MMA(ai, bj, At, Bt) do { __builtin_amdgcn_s_setprio(1); _Pragma("unroll") for (int m = 0; m < 4; ++m) _Pragma("unroll") for (int n = 0; n < 2; ++n) _Pragma("unroll") for (int k = 0; k < 2; ++k) \
;         acc[ai][bj][m][n] = __builtin_amdgcn_mfma_f32_16x16x32_f16(Bt[n][k], At[m][k], acc[ai][bj][m][n], 0, 0, 0); __builtin_amdgcn_s_setprio(0); } while (0)
; #define PG8_WAIT_V(n) asm volatile("s_waitcnt vmcnt(" #n ")" ::: "memory")
; #define PG8_WAIT_L(n) asm volatile("s_waitcnt lgkmcnt(" #n ")" ::: "memory")
; #define PG8_BAR __builtin_amdgcn_s_barrier()
; #define PG8_SCHED __builtin_amdgcn_sched_barrier(0)
; template <class Epi>
; __device__ __forceinline__ void gemm_phase(LAS unsigned char* lds, const Gemm g0, const StaticOrder& S, const Epi& E) {
;     ...
;             PG8_STAGE(PG8_SB(0, 1), b2 + hstep, voffB);
;             PG8_WAIT_V(6); PG8_BAR; PG8_MMA(1, 1, At, B1); PG8_BAR;
;             PG8_LDB(B0, 1, 0); PG8_SCHED; PG8_LDA(At, 1, 0); PG8_STAGE(PG8_SA(0, 1), a2 + hstep, voffA);
;             PG8_WAIT_L(8); PG8_BAR; PG8_WAIT_L(0); PG8_MMA(0, 0, At, B0); PG8_BAR; PG8_SCHED;
;             PG8_LDB(B1, 1, 1); PG8_STAGE(PG8_SB(1, 0), b3, voffB);
;             PG8_BAR; PG8_WAIT_L(0); PG8_MMA(0, 1, At, B1); PG8_BAR;
	s_add_u32 s22, s34, 0x80000
	s_addc_u32 s23, s35, 0
	s_add_i32 s59, s61, s19
	v_lshl_add_u64 v[142:143], s[22:23], 0, v[134:135]
	s_mov_b32 m0, s59
	s_nop 0
	global_load_lds_dwordx4 v[142:143], off
	v_lshl_add_u64 v[142:143], s[22:23], 0, v[130:131]
	s_add_i32 m0, s59, 0x2000
	s_nop 0
	global_load_lds_dwordx4 v[142:143], off
	s_waitcnt vmcnt(6)
	s_barrier
	s_setprio 0
	v_mfma_f32_16x16x32_f16 v[54:57], v[210:213], v[178:181], v[54:57]
	v_mfma_f32_16x16x32_f16 v[50:53], v[238:241], v[178:181], v[50:53]
	v_mfma_f32_16x16x32_f16 v[38:41], v[210:213], v[186:189], v[38:41]
	v_mfma_f32_16x16x32_f16 v[34:37], v[238:241], v[186:189], v[34:37]
	v_mfma_f32_16x16x32_f16 v[22:25], v[210:213], v[194:197], v[22:25]
	v_mfma_f32_16x16x32_f16 v[18:21], v[238:241], v[194:197], v[18:21]
	v_mfma_f32_16x16x32_f16 v[6:9], v[210:213], v[202:205], v[6:9]
	v_mfma_f32_16x16x32_f16 v[2:5], v[238:241], v[202:205], v[2:5]
	v_mfma_f32_16x16x32_f16 v[54:57], v[234:237], v[182:185], v[54:57]
	v_mfma_f32_16x16x32_f16 v[50:53], v[242:245], v[182:185], v[50:53]
	v_mfma_f32_16x16x32_f16 v[38:41], v[234:237], v[190:193], v[38:41]
	v_mfma_f32_16x16x32_f16 v[34:37], v[242:245], v[190:193], v[34:37]
	v_mfma_f32_16x16x32_f16 v[22:25], v[234:237], v[198:201], v[22:25]
	v_mfma_f32_16x16x32_f16 v[18:21], v[242:245], v[198:201], v[18:21]
	v_mfma_f32_16x16x32_f16 v[6:9], v[234:237], v[206:209], v[6:9]
	v_mfma_f32_16x16x32_f16 v[2:5], v[242:245], v[206:209], v[2:5]
	s_setprio 1
	s_add_i32 s59, 0, 0x18000
	v_add_u32_e32 v151, s59, v148
	s_barrier
	ds_read_b128 v[142:145], v151
	ds_read_b128 v[152:155], v151 offset:1024
	ds_read_b128 v[156:159], v151 offset:2048
	ds_read_b128 v[174:177], v151 offset:3072
	s_add_u32 s22, s36, 0x80000
	s_addc_u32 s23, s37, 0
	s_mov_b32 m0, s31
	v_lshl_add_u64 v[170:171], s[22:23], 0, v[136:137]
	ds_read_b128 v[178:181], v150 offset:32768
	ds_read_b128 v[182:185], v150 offset:33792
	ds_read_b128 v[186:189], v150 offset:34816
	ds_read_b128 v[190:193], v150 offset:35840
	ds_read_b128 v[194:197], v150 offset:36864
	ds_read_b128 v[198:201], v150 offset:37888
	ds_read_b128 v[202:205], v150 offset:38912
	ds_read_b128 v[206:209], v150 offset:39936
	global_load_lds_dwordx4 v[170:171], off
	v_lshl_add_u64 v[170:171], s[22:23], 0, v[132:133]
	s_mov_b32 m0, s38
	s_nop 0
	global_load_lds_dwordx4 v[170:171], off
	s_waitcnt lgkmcnt(8)
	s_barrier
	s_waitcnt lgkmcnt(0)
	s_setprio 0
	s_waitcnt lgkmcnt(0)
	v_mfma_f32_16x16x32_f16 v[126:129], v[142:145], v[178:181], v[126:129]
	v_mfma_f32_16x16x32_f16 v[122:125], v[156:159], v[178:181], v[122:125]
	v_mfma_f32_16x16x32_f16 v[110:113], v[142:145], v[186:189], v[110:113]
	v_mfma_f32_16x16x32_f16 v[106:109], v[156:159], v[186:189], v[106:109]
	v_mfma_f32_16x16x32_f16 v[94:97], v[142:145], v[194:197], v[94:97]
	v_mfma_f32_16x16x32_f16 v[90:93], v[156:159], v[194:197], v[90:93]
	v_mfma_f32_16x16x32_f16 v[78:81], v[142:145], v[202:205], v[78:81]
	v_mfma_f32_16x16x32_f16 v[74:77], v[156:159], v[202:205], v[74:77]
	v_mfma_f32_16x16x32_f16 v[126:129], v[152:155], v[182:185], v[126:129]
	v_mfma_f32_16x16x32_f16 v[122:125], v[174:177], v[182:185], v[122:125]
	v_mfma_f32_16x16x32_f16 v[110:113], v[152:155], v[190:193], v[110:113]
	v_mfma_f32_16x16x32_f16 v[106:109], v[174:177], v[190:193], v[106:109]
	v_mfma_f32_16x16x32_f16 v[94:97], v[152:155], v[198:201], v[94:97]
	v_mfma_f32_16x16x32_f16 v[90:93], v[174:177], v[198:201], v[90:93]
	v_mfma_f32_16x16x32_f16 v[78:81], v[152:155], v[206:209], v[78:81]
	v_mfma_f32_16x16x32_f16 v[74:77], v[174:177], v[206:209], v[74:77]
	s_setprio 1
	s_barrier
	s_add_i32 s36, 0, 0x1c000
	s_add_i32 s22, s59, s19
	v_add_u32_e32 v151, s36, v148
	v_lshl_add_u64 v[146:147], v[146:147], 0, s[64:65]
	s_mov_b32 m0, s22
	ds_read_b128 v[210:213], v151
	ds_read_b128 v[234:237], v151 offset:1024
	ds_read_b128 v[238:241], v151 offset:2048
	ds_read_b128 v[242:245], v151 offset:3072
	global_load_lds_dwordx4 v[146:147], off
	v_lshl_add_u64 v[146:147], v[160:161], 0, s[64:65]
	s_add_i32 m0, s22, 0x2000
	s_nop 0
	global_load_lds_dwordx4 v[146:147], off
	s_barrier
	s_waitcnt lgkmcnt(0)
	s_setprio 0
	s_waitcnt lgkmcnt(0)
	v_mfma_f32_16x16x32_f16 v[118:121], v[210:213], v[178:181], v[118:121]
	v_mfma_f32_16x16x32_f16 v[114:117], v[238:241], v[178:181], v[114:117]
	v_mfma_f32_16x16x32_f16 v[102:105], v[210:213], v[186:189], v[102:105]
	v_mfma_f32_16x16x32_f16 v[98:101], v[238:241], v[186:189], v[98:101]
	v_mfma_f32_16x16x32_f16 v[86:89], v[210:213], v[194:197], v[86:89]
	v_mfma_f32_16x16x32_f16 v[82:85], v[238:241], v[194:197], v[82:85]
	v_mfma_f32_16x16x32_f16 v[70:73], v[210:213], v[202:205], v[70:73]
	v_mfma_f32_16x16x32_f16 v[66:69], v[238:241], v[202:205], v[66:69]
	v_mfma_f32_16x16x32_f16 v[118:121], v[234:237], v[182:185], v[118:121]
	v_mfma_f32_16x16x32_f16 v[114:117], v[242:245], v[182:185], v[114:117]
	v_mfma_f32_16x16x32_f16 v[102:105], v[234:237], v[190:193], v[102:105]
	v_mfma_f32_16x16x32_f16 v[98:101], v[242:245], v[190:193], v[98:101]
	v_mfma_f32_16x16x32_f16 v[86:89], v[234:237], v[198:201], v[86:89]
	v_mfma_f32_16x16x32_f16 v[82:85], v[242:245], v[198:201], v[82:85]
	v_mfma_f32_16x16x32_f16 v[70:73], v[234:237], v[206:209], v[70:73]
	v_mfma_f32_16x16x32_f16 v[66:69], v[242:245], v[206:209], v[66:69]
	s_setprio 1
	s_mov_b32 m0, s39
	v_lshl_add_u64 v[146:147], v[162:163], 0, s[64:65]
	s_barrier
; __device__ __forceinline__ float gelu_tanh(float x) { const float y = 1.5957691216057308f * (x + 0.044715f * x * x * x); return x * fast_rcp(1.0f + __expf(-y)); }
; #define PG8_STAGE(bufoff, gbase, voff) do { _Pragma("unroll") for (int _i = 0; _i < 2; ++_i) \
;         __builtin_amdgcn_global_load_lds((const unsigned*)((const char*)(gbase) + (voff)[_i]), (LAS unsigned*)(lds + (bufoff) + ldsw + _i * 8192), 16, 0, 0); } while (0)
; #define PG8_LDA(dst, b, h) do { _Pragma("unroll") for (int m = 0; m < 4; ++m) _Pragma("unroll") for (int k = 0; k < 2; ++k) dst[m][k] = *(const LAS f16x8*)(lds + PG8_SA(b, h) + aoff + m * 2048 + k * 1024); } while (0)
; #define PG8_MMA(ai, bj, At, Bt) do { __builtin_amdgcn_s_setprio(1); _Pragma("unroll") for (int m = 0; m < 4; ++m) _Pragma("unroll") for (int n = 0; n < 2; ++n) _Pragma("unroll") for (int k = 0; k < 2; ++k) \
;         acc[ai][bj][m][n] = __builtin_amdgcn_mfma_f32_16x16x32_f16(Bt[n][k], At[m][k], acc[ai][bj][m][n], 0, 0, 0); __builtin_amdgcn_s_setprio(0); } while (0)
; #define PG8_WAIT_V(n) asm volatile("s_waitcnt vmcnt(" #n ")" ::: "memory")
; #define PG8_WAIT_L(n) asm volatile("s_waitcnt lgkmcnt(" #n ")" ::: "memory")
; #define PG8_BAR __builtin_amdgcn_s_barrier()
; #define PG8_SCHED __builtin_amdgcn_sched_barrier(0)
;     __device__ __forceinline__ void operator()(f32x4 (&acc)[2][2][4][2], const Unit& u, int wr, int wc, int fr, int fq) const {
;     ...
;                 for (int bj = 0; bj < 2; ++bj) { f32x4 v0 = acc[ai][bj][m][0], v1 = acc[ai][bj][m][1];
;                     if (isy) {
; #pragma unroll
;                         for (int j = 0; j < 4; ++j) { v0[j] = gelu_tanh(v0[j]); v1[j] = gelu_tanh(v1[j]); } }
; template <class Epi>
; __device__ __forceinline__ void gemm_phase(LAS unsigned char* lds, const Gemm g0, const StaticOrder& S, const Epi& E) {
;     ...
;             PG8_LDA(At, 1, 1); PG8_STAGE(PG8_SA(1, 0), a3, voffA);
;             PG8_BAR; PG8_WAIT_L(0); PG8_MMA(1, 0, At, B0); PG8_BAR; PG8_SCHED;
;             PG8_STAGE(PG8_SB(1, 1), b3 + hstep, voffB);
;             PG8_WAIT_V(6); PG8_BAR; PG8_MMA(1, 1, At, B1); PG8_BAR;
;         }
	ds_read_b128 v[178:181], v150 offset:49152
	ds_read_b128 v[182:185], v150 offset:50176
	ds_read_b128 v[186:189], v150 offset:51200
	ds_read_b128 v[190:193], v150 offset:52224
	ds_read_b128 v[194:197], v150 offset:53248
	ds_read_b128 v[198:201], v150 offset:54272
	ds_read_b128 v[202:205], v150 offset:55296
	ds_read_b128 v[206:209], v150 offset:56320
	global_load_lds_dwordx4 v[146:147], off
	v_lshl_add_u64 v[146:147], v[164:165], 0, s[64:65]
	s_mov_b32 m0, s48
	s_nop 0
	global_load_lds_dwordx4 v[146:147], off
	s_barrier
	s_waitcnt lgkmcnt(0)
	s_setprio 0
	s_waitcnt lgkmcnt(0)
	v_mfma_f32_16x16x32_f16 v[62:65], v[142:145], v[178:181], v[62:65]
	v_mfma_f32_16x16x32_f16 v[58:61], v[156:159], v[178:181], v[58:61]
	v_mfma_f32_16x16x32_f16 v[46:49], v[142:145], v[186:189], v[46:49]
	v_mfma_f32_16x16x32_f16 v[42:45], v[156:159], v[186:189], v[42:45]
	v_mfma_f32_16x16x32_f16 v[30:33], v[142:145], v[194:197], v[30:33]
	v_mfma_f32_16x16x32_f16 v[26:29], v[156:159], v[194:197], v[26:29]
	v_mfma_f32_16x16x32_f16 v[14:17], v[142:145], v[202:205], v[14:17]
	v_mfma_f32_16x16x32_f16 v[10:13], v[156:159], v[202:205], v[10:13]
	v_mfma_f32_16x16x32_f16 v[62:65], v[152:155], v[182:185], v[62:65]
	v_mfma_f32_16x16x32_f16 v[58:61], v[174:177], v[182:185], v[58:61]
	v_mfma_f32_16x16x32_f16 v[46:49], v[152:155], v[190:193], v[46:49]
	v_mfma_f32_16x16x32_f16 v[42:45], v[174:177], v[190:193], v[42:45]
	v_mfma_f32_16x16x32_f16 v[30:33], v[152:155], v[198:201], v[30:33]
	v_mfma_f32_16x16x32_f16 v[26:29], v[174:177], v[198:201], v[26:29]
	v_mfma_f32_16x16x32_f16 v[14:17], v[152:155], v[206:209], v[14:17]
	v_mfma_f32_16x16x32_f16 v[10:13], v[174:177], v[206:209], v[10:13]
	s_setprio 1
	s_barrier
	s_add_u32 s22, s34, 0x80080
	s_addc_u32 s23, s35, 0
	s_add_i32 s34, s36, s19
	v_lshl_add_u64 v[142:143], s[22:23], 0, v[134:135]
	s_mov_b32 m0, s34
	s_nop 0
	global_load_lds_dwordx4 v[142:143], off
	v_lshl_add_u64 v[142:143], s[22:23], 0, v[130:131]
	s_add_i32 m0, s34, 0x2000
	s_nop 0
	global_load_lds_dwordx4 v[142:143], off
	s_waitcnt vmcnt(6)
	s_barrier
	s_setprio 0
	v_mfma_f32_16x16x32_f16 v[54:57], v[210:213], v[178:181], v[54:57]
	v_mfma_f32_16x16x32_f16 v[50:53], v[238:241], v[178:181], v[50:53]
	v_mfma_f32_16x16x32_f16 v[38:41], v[210:213], v[186:189], v[38:41]
	v_mfma_f32_16x16x32_f16 v[34:37], v[238:241], v[186:189], v[34:37]
	v_mfma_f32_16x16x32_f16 v[22:25], v[210:213], v[194:197], v[22:25]
	v_mfma_f32_16x16x32_f16 v[18:21], v[238:241], v[194:197], v[18:21]
	v_mfma_f32_16x16x32_f16 v[6:9], v[210:213], v[202:205], v[6:9]
	v_mfma_f32_16x16x32_f16 v[2:5], v[238:241], v[202:205], v[2:5]
	v_mfma_f32_16x16x32_f16 v[54:57], v[234:237], v[182:185], v[54:57]
	v_mfma_f32_16x16x32_f16 v[50:53], v[242:245], v[182:185], v[50:53]
	v_mfma_f32_16x16x32_f16 v[38:41], v[234:237], v[190:193], v[38:41]
	v_mfma_f32_16x16x32_f16 v[34:37], v[242:245], v[190:193], v[34:37]
	v_mfma_f32_16x16x32_f16 v[22:25], v[234:237], v[198:201], v[22:25]
	v_mfma_f32_16x16x32_f16 v[18:21], v[242:245], v[198:201], v[18:21]
	v_mfma_f32_16x16x32_f16 v[6:9], v[234:237], v[206:209], v[6:9]
	v_mfma_f32_16x16x32_f16 v[2:5], v[242:245], v[206:209], v[2:5]
	s_setprio 1
	s_add_i32 s58, s58, 2
	s_add_u32 s25, s25, 0x100
	s_addc_u32 s53, s53, 0
	s_add_u32 s6, s6, 0x100
	s_addc_u32 s7, s7, 0
	s_cmp_gt_u32 s58, 29
	s_barrier
	s_cbranch_scc0 .LBB0_302
	s_cmp_lt_i32 s51, 8
	s_cselect_b64 s[34:35], -1, 0
	s_cmp_gt_i32 s51, 7
	s_cbranch_scc1 .LBB0_305
	v_mul_f32_e32 v143, 0x3d372713, v122
	v_mul_f32_e32 v143, v122, v143
	v_fma_f32 v143, v122, v143, v122
	v_mul_f32_e32 v143, 0xbfcc422a, v143
	v_mul_f32_e32 v143, 0x3fb8aa3b, v143
	v_exp_f32_e32 v143, v143
	v_mul_f32_e32 v142, 0x3d372713, v126
	v_mul_f32_e32 v142, v126, v142
	v_fma_f32 v142, v126, v142, v126
	v_add_f32_e32 v143, 1.0, v143
	v_rcp_f32_e32 v144, v143
	v_mul_f32_e32 v143, 0x3d372713, v127
	v_mul_f32_e32 v143, v127, v143
	v_fma_f32 v143, v127, v143, v127
	v_mul_f32_e32 v142, 0xbfcc422a, v142
	v_mul_f32_e32 v143, 0xbfcc422a, v143
	v_mul_f32_e32 v142, 0x3fb8aa3b, v142
	v_mul_f32_e32 v143, 0x3fb8aa3b, v143
	v_mul_f32_e32 v147, 0x3d372713, v124
	v_exp_f32_e32 v142, v142
	v_exp_f32_e32 v143, v143
	v_mul_f32_e32 v147, v124, v147
	v_fma_f32 v147, v124, v147, v124
	v_mul_f32_e32 v147, 0xbfcc422a, v147
	v_mul_f32_e32 v147, 0x3fb8aa3b, v147
	v_add_f32_e32 v142, 1.0, v142
	v_add_f32_e32 v143, 1.0, v143
	v_exp_f32_e32 v147, v147
	v_rcp_f32_e32 v142, v142
	v_rcp_f32_e32 v143, v143
	v_mul_f32_e32 v145, 0x3d372713, v123
	v_add_f32_e32 v147, 1.0, v147
	v_mul_f32_e32 v146, 0x3d372713, v128
	v_rcp_f32_e32 v152, v147
	v_mul_f32_e32 v147, 0x3d372713, v129
	v_pk_mul_f32 v[126:127], v[126:127], v[142:143]
	v_mul_f32_e32 v142, 0x3d372713, v125
	v_mul_f32_e32 v145, v123, v145
	v_mul_f32_e32 v146, v128, v146
	v_mul_f32_e32 v147, v129, v147
	v_mul_f32_e32 v142, v125, v142
	v_fma_f32 v145, v123, v145, v123
	v_fma_f32 v146, v128, v146, v128
	v_fma_f32 v147, v129, v147, v129
	v_fma_f32 v142, v125, v142, v125
	v_mul_f32_e32 v145, 0xbfcc422a, v145
	v_mul_f32_e32 v146, 0xbfcc422a, v146
	v_mul_f32_e32 v147, 0xbfcc422a, v147
	v_mul_f32_e32 v142, 0xbfcc422a, v142
	v_mul_f32_e32 v145, 0x3fb8aa3b, v145
	v_mul_f32_e32 v146, 0x3fb8aa3b, v146
	v_mul_f32_e32 v147, 0x3fb8aa3b, v147
	v_mul_f32_e32 v142, 0x3fb8aa3b, v142
	v_exp_f32_e32 v145, v145
	v_exp_f32_e32 v146, v146
	v_exp_f32_e32 v147, v147
	v_exp_f32_e32 v142, v142
	v_add_f32_e32 v145, 1.0, v145
	v_add_f32_e32 v146, 1.0, v146
	v_add_f32_e32 v147, 1.0, v147
	v_add_f32_e32 v142, 1.0, v142
	v_rcp_f32_e32 v145, v145
	v_rcp_f32_e32 v146, v146
	v_rcp_f32_e32 v147, v147
	v_rcp_f32_e32 v153, v142
	v_pk_mul_f32 v[122:123], v[122:123], v[144:145]
	v_pk_mul_f32 v[128:129], v[128:129], v[146:147]
	v_pk_mul_f32 v[124:125], v[124:125], v[152:153]

;     __device__ __forceinline__ void prefetch(const Unit& u, int wr, int wc, int lane) const { lnfold_prefetch(vl, stats, gW, bW, u, wr, wc, lane); }
;     __device__ __forceinline__ void prefetch(const Unit& u, int wr, int wc, int lane) const { lnfold_prefetch(vl, stats, gW, bW, u, wr, wc, lane); }
; #define PG8_STAGE(bufoff, gbase, voff) do { _Pragma("unroll") for (int _i = 0; _i < 2; ++_i) \
;         __builtin_amdgcn_global_load_lds((const unsigned*)((const char*)(gbase) + (voff)[_i]), (LAS unsigned*)(lds + (bufoff) + ldsw + _i * 8192), 16, 0, 0); } while (0)
; #define PG8_LDA(dst, b, h) do { _Pragma("unroll") for (int m = 0; m < 4; ++m) _Pragma("unroll") for (int k = 0; k < 2; ++k) dst[m][k] = *(const LAS f16x8*)(lds + PG8_SA(b, h) + aoff + m * 2048 + k * 1024); } while (0)
; #define PG8_LDB(dst, b, h) do { _Pragma("unroll") for (int n = 0; n < 2; ++n) _Pragma("unroll") for (int k = 0; k < 2; ++k) dst[n][k] = *(const LAS f16x8*)(lds + PG8_SB(b, h) + boff + n * 2048 + k * 1024); } while (0)
; #define PG8_MMA(ai, bj, At, Bt) do { __builtin_amdgcn_s_setprio(1); _Pragma("unroll") for (int m = 0; m < 4; ++m) _Pragma("unroll") for (int n = 0; n < 2; ++n) _Pragma("unroll") for (int k = 0; k < 2; ++k) \
;         acc[ai][bj][m][n] = __builtin_amdgcn_mfma_f32_16x16x32_f16(Bt[n][k], At[m][k], acc[ai][bj][m][n], 0, 0, 0); __builtin_amdgcn_s_setprio(0); } while (0)
; template <class Epi>
; __device__ __forceinline__ void gemm_phase(LAS unsigned char* lds, const Gemm g0, const StaticOrder& S, const Epi& E) {
;     ...
;             const bool last = (t == nt - 2);
;             if (Epi::PREF && last) E.prefetch(cur, wr, wc, lane);
;             const char* a1 = cA + (size_t)(t + 1) * kstep;
;             const char* a2 = last ? nA : cA + (size_t)(t + 2) * kstep; const char* b2 = last ? nB : cB + (size_t)(t + 2) * kstep;
;             const char* a3 = a2 + kstep; const char* b3 = b2 + kstep;
;             PG8_LDB(B0, 0, 0); PG8_SCHED; PG8_LDA(At, 0, 0); PG8_STAGE(PG8_SA(1, 1), a1 + hstep, voffA);
;             PG8_WAIT_L(8); PG8_BAR; PG8_WAIT_L(0); PG8_MMA(0, 0, At, B0); PG8_BAR; PG8_SCHED;
;             PG8_LDB(B1, 0, 1); PG8_STAGE(PG8_SB(0, 0), b2, voffB);
;             PG8_BAR; PG8_WAIT_L(0); PG8_MMA(0, 1, At, B1); PG8_BAR;
;             PG8_LDA(At, 0, 1); PG8_STAGE(PG8_SA(0, 0), a2, voffA);
;             PG8_BAR; PG8_WAIT_L(0); PG8_MMA(1, 0, At, B0); PG8_BAR; PG8_SCHED;
.LBB0_512:
	s_add_u32 s23, s12, 0xfff80080
	s_addc_u32 s48, s13, -1
	s_add_i32 s90, 0, 0x10000
	v_add_u32_e32 v142, s90, v205
	ds_read_b128 v[122:125], v142
	ds_read_b128 v[126:129], v142 offset:1024
	ds_read_b128 v[138:141], v142 offset:2048
	ds_read_b128 v[142:145], v142 offset:3072
	s_cmp_eq_u32 s22, 28
	s_cselect_b32 s51, s15, s48
	s_cselect_b32 s50, s24, s23
	s_cselect_b32 s49, s25, vcc_hi
	s_cselect_b32 s48, s53, vcc_lo
	v_lshl_add_u64 v[162:163], s[12:13], 0, v[186:187]
	s_add_i32 m0, s71, 0xc000
	ds_read_b128 v[146:149], v210
	ds_read_b128 v[150:153], v210 offset:1024
	ds_read_b128 v[154:157], v210 offset:2048
	ds_read_b128 v[158:161], v210 offset:3072
	ds_read_b128 v[188:191], v210 offset:4096
	ds_read_b128 v[192:195], v210 offset:5120
	ds_read_b128 v[196:199], v210 offset:6144
	ds_read_b128 v[200:203], v210 offset:7168
	global_load_lds_dwordx4 v[162:163], off
	v_lshl_add_u64 v[162:163], s[12:13], 0, v[184:185]
	s_add_i32 m0, s71, 0xe000
	s_nop 0
	global_load_lds_dwordx4 v[162:163], off
	s_waitcnt lgkmcnt(8)
	s_barrier
	s_waitcnt lgkmcnt(0)
	s_setprio 0
	s_waitcnt lgkmcnt(0)
	v_mfma_f32_16x16x32_f16 v[134:137], v[122:125], v[146:149], v[134:137]
	v_mfma_f32_16x16x32_f16 v[130:133], v[138:141], v[146:149], v[130:133]
	v_mfma_f32_16x16x32_f16 v[110:113], v[122:125], v[154:157], v[110:113]
	v_mfma_f32_16x16x32_f16 v[106:109], v[138:141], v[154:157], v[106:109]
	v_mfma_f32_16x16x32_f16 v[94:97], v[122:125], v[188:191], v[94:97]
	v_mfma_f32_16x16x32_f16 v[90:93], v[138:141], v[188:191], v[90:93]
	v_mfma_f32_16x16x32_f16 v[78:81], v[122:125], v[196:199], v[78:81]
	v_mfma_f32_16x16x32_f16 v[74:77], v[138:141], v[196:199], v[74:77]
	v_mfma_f32_16x16x32_f16 v[134:137], v[126:129], v[150:153], v[134:137]
	v_mfma_f32_16x16x32_f16 v[130:133], v[142:145], v[150:153], v[130:133]
	v_mfma_f32_16x16x32_f16 v[110:113], v[126:129], v[158:161], v[110:113]
	v_mfma_f32_16x16x32_f16 v[106:109], v[142:145], v[158:161], v[106:109]
	v_mfma_f32_16x16x32_f16 v[94:97], v[126:129], v[192:195], v[94:97]
	v_mfma_f32_16x16x32_f16 v[90:93], v[142:145], v[192:195], v[90:93]
	v_mfma_f32_16x16x32_f16 v[78:81], v[126:129], v[200:203], v[78:81]
	v_mfma_f32_16x16x32_f16 v[74:77], v[142:145], v[200:203], v[74:77]
	s_setprio 1
	s_barrier
	s_add_i32 s23, 0, 0x14000
	v_add_u32_e32 v162, s23, v205
	s_add_i32 s90, s90, s75
	ds_read_b128 v[212:215], v162
	ds_read_b128 v[234:237], v162 offset:1024
	ds_read_b128 v[238:241], v162 offset:2048
	ds_read_b128 v[242:245], v162 offset:3072
	v_lshl_add_u64 v[162:163], s[48:49], 0, v[178:179]
	s_mov_b32 m0, s90
	v_lshl_add_u64 v[164:165], s[48:49], 0, v[174:175]
	global_load_lds_dwordx4 v[162:163], off
	s_add_i32 m0, s90, 0x2000
	s_nop 0
	global_load_lds_dwordx4 v[164:165], off
	s_barrier
	s_waitcnt lgkmcnt(0)
	s_setprio 0
	s_waitcnt lgkmcnt(0)
	v_mfma_f32_16x16x32_f16 v[118:121], v[212:215], v[146:149], v[118:121]
	v_mfma_f32_16x16x32_f16 v[114:117], v[238:241], v[146:149], v[114:117]
	v_mfma_f32_16x16x32_f16 v[102:105], v[212:215], v[154:157], v[102:105]
	v_mfma_f32_16x16x32_f16 v[98:101], v[238:241], v[154:157], v[98:101]
	v_mfma_f32_16x16x32_f16 v[86:89], v[212:215], v[188:191], v[86:89]
	v_mfma_f32_16x16x32_f16 v[82:85], v[238:241], v[188:191], v[82:85]
	v_mfma_f32_16x16x32_f16 v[70:73], v[212:215], v[196:199], v[70:73]
	v_mfma_f32_16x16x32_f16 v[66:69], v[238:241], v[196:199], v[66:69]
	v_mfma_f32_16x16x32_f16 v[118:121], v[234:237], v[150:153], v[118:121]
	v_mfma_f32_16x16x32_f16 v[114:117], v[242:245], v[150:153], v[114:117]
	v_mfma_f32_16x16x32_f16 v[102:105], v[234:237], v[158:161], v[102:105]
	v_mfma_f32_16x16x32_f16 v[98:101], v[242:245], v[158:161], v[98:101]
	v_mfma_f32_16x16x32_f16 v[86:89], v[234:237], v[192:195], v[86:89]
	v_mfma_f32_16x16x32_f16 v[82:85], v[242:245], v[192:195], v[82:85]
	v_mfma_f32_16x16x32_f16 v[70:73], v[234:237], v[200:203], v[70:73]
	v_mfma_f32_16x16x32_f16 v[66:69], v[242:245], v[200:203], v[66:69]
	s_setprio 1
	s_mov_b32 m0, s71
	v_lshl_add_u64 v[170:171], s[50:51], 0, v[180:181]
	s_barrier
	ds_read_b128 v[146:149], v210 offset:16384
	ds_read_b128 v[150:153], v210 offset:17408
	ds_read_b128 v[154:157], v210 offset:18432
	ds_read_b128 v[158:161], v210 offset:19456
	ds_read_b128 v[188:191], v210 offset:20480
	ds_read_b128 v[192:195], v210 offset:21504
	ds_read_b128 v[196:199], v210 offset:22528
	ds_read_b128 v[200:203], v210 offset:23552
	global_load_lds_dwordx4 v[170:171], off
	v_lshl_add_u64 v[172:173], s[50:51], 0, v[176:177]
	s_mov_b32 m0, s61
	s_nop 0
	global_load_lds_dwordx4 v[172:173], off
	s_barrier
	s_waitcnt lgkmcnt(0)
	s_setprio 0
	s_waitcnt lgkmcnt(0)
	v_mfma_f32_16x16x32_f16 v[62:65], v[122:125], v[146:149], v[62:65]
	v_mfma_f32_16x16x32_f16 v[58:61], v[138:141], v[146:149], v[58:61]
	v_mfma_f32_16x16x32_f16 v[46:49], v[122:125], v[154:157], v[46:49]
	v_mfma_f32_16x16x32_f16 v[42:45], v[138:141], v[154:157], v[42:45]
	v_mfma_f32_16x16x32_f16 v[30:33], v[122:125], v[188:191], v[30:33]
	v_mfma_f32_16x16x32_f16 v[26:29], v[138:141], v[188:191], v[26:29]
	v_mfma_f32_16x16x32_f16 v[14:17], v[122:125], v[196:199], v[14:17]
	v_mfma_f32_16x16x32_f16 v[10:13], v[138:141], v[196:199], v[10:13]
	v_mfma_f32_16x16x32_f16 v[62:65], v[126:129], v[150:153], v[62:65]
	v_mfma_f32_16x16x32_f16 v[58:61], v[142:145], v[150:153], v[58:61]
	v_mfma_f32_16x16x32_f16 v[46:49], v[126:129], v[158:161], v[46:49]
	v_mfma_f32_16x16x32_f16 v[42:45], v[142:145], v[158:161], v[42:45]
	v_mfma_f32_16x16x32_f16 v[30:33], v[126:129], v[192:195], v[30:33]
	v_mfma_f32_16x16x32_f16 v[26:29], v[142:145], v[192:195], v[26:29]
	v_mfma_f32_16x16x32_f16 v[14:17], v[126:129], v[200:203], v[14:17]
	v_mfma_f32_16x16x32_f16 v[10:13], v[142:145], v[200:203], v[10:13]
	s_setprio 1
	s_barrier
; #define PG8_STAGE(bufoff, gbase, voff) do { _Pragma("unroll") for (int _i = 0; _i < 2; ++_i) \
;         __builtin_amdgcn_global_load_lds((const unsigned*)((const char*)(gbase) + (voff)[_i]), (LAS unsigned*)(lds + (bufoff) + ldsw + _i * 8192), 16, 0, 0); } while (0)
; #define PG8_LDA(dst, b, h) do { _Pragma("unroll") for (int m = 0; m < 4; ++m) _Pragma("unroll") for (int k = 0; k < 2; ++k) dst[m][k] = *(const LAS f16x8*)(lds + PG8_SA(b, h) + aoff + m * 2048 + k * 1024); } while (0)
; #define PG8_LDB(dst, b, h) do { _Pragma("unroll") for (int n = 0; n < 2; ++n) _Pragma("unroll") for (int k = 0; k < 2; ++k) dst[n][k] = *(const LAS f16x8*)(lds + PG8_SB(b, h) + boff + n * 2048 + k * 1024); } while (0)
; #define PG8_MMA(ai, bj, At, Bt) do { __builtin_amdgcn_s_setprio(1); _Pragma("unroll") for (int m = 0; m < 4; ++m) _Pragma("unroll") for (int n = 0; n < 2; ++n) _Pragma("unroll") for (int k = 0; k < 2; ++k) \
;         acc[ai][bj][m][n] = __builtin_amdgcn_mfma_f32_16x16x32_f16(Bt[n][k], At[m][k], acc[ai][bj][m][n], 0, 0, 0); __builtin_amdgcn_s_setprio(0); } while (0)
; #define PG8_WAIT_V(n) asm volatile("s_waitcnt vmcnt(" #n ")" ::: "memory")
; #define PG8_WAIT_L(n) asm volatile("s_waitcnt lgkmcnt(" #n ")" ::: "memory")
; #define PG8_BAR __builtin_amdgcn_s_barrier()
; #define PG8_SCHED __builtin_amdgcn_sched_barrier(0)
; template <class Epi>
; __device__ __forceinline__ void gemm_phase(LAS unsigned char* lds, const Gemm g0, const StaticOrder& S, const Epi& E) {
;     ...
;             PG8_STAGE(PG8_SB(0, 1), b2 + hstep, voffB);
;             PG8_WAIT_V(6); PG8_BAR; PG8_MMA(1, 1, At, B1); PG8_BAR;
;             PG8_LDB(B0, 1, 0); PG8_SCHED; PG8_LDA(At, 1, 0); PG8_STAGE(PG8_SA(0, 1), a2 + hstep, voffA);
;             PG8_WAIT_L(8); PG8_BAR; PG8_WAIT_L(0); PG8_MMA(0, 0, At, B0); PG8_BAR; PG8_SCHED;
;             PG8_LDB(B1, 1, 1); PG8_STAGE(PG8_SB(1, 0), b3, voffB);
;             PG8_BAR; PG8_WAIT_L(0); PG8_MMA(0, 1, At, B1); PG8_BAR;
	s_add_u32 s90, s48, 0x80000
	s_addc_u32 s91, s49, 0
	s_add_i32 s23, s23, s75
	v_lshl_add_u64 v[122:123], s[90:91], 0, v[178:179]
	s_mov_b32 m0, s23
	s_nop 0
	global_load_lds_dwordx4 v[122:123], off
	v_lshl_add_u64 v[122:123], s[90:91], 0, v[174:175]
	s_add_i32 m0, s23, 0x2000
	s_nop 0
	global_load_lds_dwordx4 v[122:123], off
	s_waitcnt vmcnt(6)
	s_barrier
	s_setprio 0
	v_mfma_f32_16x16x32_f16 v[54:57], v[212:215], v[146:149], v[54:57]
	v_mfma_f32_16x16x32_f16 v[50:53], v[238:241], v[146:149], v[50:53]
	v_mfma_f32_16x16x32_f16 v[38:41], v[212:215], v[154:157], v[38:41]
	v_mfma_f32_16x16x32_f16 v[34:37], v[238:241], v[154:157], v[34:37]
	v_mfma_f32_16x16x32_f16 v[22:25], v[212:215], v[188:191], v[22:25]
	v_mfma_f32_16x16x32_f16 v[18:21], v[238:241], v[188:191], v[18:21]
	v_mfma_f32_16x16x32_f16 v[6:9], v[212:215], v[196:199], v[6:9]
	v_mfma_f32_16x16x32_f16 v[2:5], v[238:241], v[196:199], v[2:5]
	v_mfma_f32_16x16x32_f16 v[54:57], v[234:237], v[150:153], v[54:57]
	v_mfma_f32_16x16x32_f16 v[50:53], v[242:245], v[150:153], v[50:53]
	v_mfma_f32_16x16x32_f16 v[38:41], v[234:237], v[158:161], v[38:41]
	v_mfma_f32_16x16x32_f16 v[34:37], v[242:245], v[158:161], v[34:37]
	v_mfma_f32_16x16x32_f16 v[22:25], v[234:237], v[192:195], v[22:25]
	v_mfma_f32_16x16x32_f16 v[18:21], v[242:245], v[192:195], v[18:21]
	v_mfma_f32_16x16x32_f16 v[6:9], v[234:237], v[200:203], v[6:9]
	v_mfma_f32_16x16x32_f16 v[2:5], v[242:245], v[200:203], v[2:5]
	s_setprio 1
	s_add_i32 s23, 0, 0x18000
	v_add_u32_e32 v142, s23, v205
	s_barrier
	ds_read_b128 v[122:125], v142
	ds_read_b128 v[126:129], v142 offset:1024
	ds_read_b128 v[138:141], v142 offset:2048
	ds_read_b128 v[142:145], v142 offset:3072
	s_add_u32 s50, s50, 0x80000
	s_addc_u32 s51, s51, 0
	s_mov_b32 m0, s74
	v_lshl_add_u64 v[212:213], s[50:51], 0, v[180:181]
	ds_read_b128 v[146:149], v210 offset:32768
	ds_read_b128 v[150:153], v210 offset:33792
	ds_read_b128 v[154:157], v210 offset:34816
	ds_read_b128 v[158:161], v210 offset:35840
	ds_read_b128 v[188:191], v210 offset:36864
	ds_read_b128 v[192:195], v210 offset:37888
	ds_read_b128 v[196:199], v210 offset:38912
	ds_read_b128 v[200:203], v210 offset:39936
	global_load_lds_dwordx4 v[212:213], off
	v_lshl_add_u64 v[212:213], s[50:51], 0, v[176:177]
	s_mov_b32 m0, s18
	s_nop 0
	global_load_lds_dwordx4 v[212:213], off
	s_waitcnt lgkmcnt(8)
	s_barrier
	s_waitcnt lgkmcnt(0)
	s_setprio 0
	s_waitcnt lgkmcnt(0)
	v_mfma_f32_16x16x32_f16 v[134:137], v[122:125], v[146:149], v[134:137]
	v_mfma_f32_16x16x32_f16 v[130:133], v[138:141], v[146:149], v[130:133]
	v_mfma_f32_16x16x32_f16 v[110:113], v[122:125], v[154:157], v[110:113]
	v_mfma_f32_16x16x32_f16 v[106:109], v[138:141], v[154:157], v[106:109]
	v_mfma_f32_16x16x32_f16 v[94:97], v[122:125], v[188:191], v[94:97]
	v_mfma_f32_16x16x32_f16 v[90:93], v[138:141], v[188:191], v[90:93]
	v_mfma_f32_16x16x32_f16 v[78:81], v[122:125], v[196:199], v[78:81]
	v_mfma_f32_16x16x32_f16 v[74:77], v[138:141], v[196:199], v[74:77]
	v_mfma_f32_16x16x32_f16 v[134:137], v[126:129], v[150:153], v[134:137]
	v_mfma_f32_16x16x32_f16 v[130:133], v[142:145], v[150:153], v[130:133]
	v_mfma_f32_16x16x32_f16 v[110:113], v[126:129], v[158:161], v[110:113]
	v_mfma_f32_16x16x32_f16 v[106:109], v[142:145], v[158:161], v[106:109]
	v_mfma_f32_16x16x32_f16 v[94:97], v[126:129], v[192:195], v[94:97]
	v_mfma_f32_16x16x32_f16 v[90:93], v[142:145], v[192:195], v[90:93]
	v_mfma_f32_16x16x32_f16 v[78:81], v[126:129], v[200:203], v[78:81]
	v_mfma_f32_16x16x32_f16 v[74:77], v[142:145], v[200:203], v[74:77]
	s_setprio 1
	s_barrier
	s_add_i32 s50, 0, 0x1c000
	s_add_i32 s23, s23, s75
	v_add_u32_e32 v211, s50, v205
	v_lshl_add_u64 v[162:163], v[162:163], 0, s[64:65]
	s_mov_b32 m0, s23
	ds_read_b128 v[212:215], v211
	ds_read_b128 v[234:237], v211 offset:1024
	ds_read_b128 v[238:241], v211 offset:2048
	ds_read_b128 v[242:245], v211 offset:3072
	global_load_lds_dwordx4 v[162:163], off
	v_lshl_add_u64 v[162:163], v[164:165], 0, s[64:65]
	s_add_i32 m0, s23, 0x2000
	s_nop 0
	global_load_lds_dwordx4 v[162:163], off
	s_barrier
; #define GAS __attribute__((address_space(1)))
; #define PG8_STAGE(bufoff, gbase, voff) do { _Pragma("unroll") for (int _i = 0; _i < 2; ++_i) \
;         __builtin_amdgcn_global_load_lds((const unsigned*)((const char*)(gbase) + (voff)[_i]), (LAS unsigned*)(lds + (bufoff) + ldsw + _i * 8192), 16, 0, 0); } while (0)
; #define PG8_LDA(dst, b, h) do { _Pragma("unroll") for (int m = 0; m < 4; ++m) _Pragma("unroll") for (int k = 0; k < 2; ++k) dst[m][k] = *(const LAS f16x8*)(lds + PG8_SA(b, h) + aoff + m * 2048 + k * 1024); } while (0)
; #define PG8_MMA(ai, bj, At, Bt) do { __builtin_amdgcn_s_setprio(1); _Pragma("unroll") for (int m = 0; m < 4; ++m) _Pragma("unroll") for (int n = 0; n < 2; ++n) _Pragma("unroll") for (int k = 0; k < 2; ++k) \
;         acc[ai][bj][m][n] = __builtin_amdgcn_mfma_f32_16x16x32_f16(Bt[n][k], At[m][k], acc[ai][bj][m][n], 0, 0, 0); __builtin_amdgcn_s_setprio(0); } while (0)
; #define PG8_WAIT_V(n) asm volatile("s_waitcnt vmcnt(" #n ")" ::: "memory")
; #define PG8_WAIT_L(n) asm volatile("s_waitcnt lgkmcnt(" #n ")" ::: "memory")
; #define PG8_BAR __builtin_amdgcn_s_barrier()
; #define PG8_SCHED __builtin_amdgcn_sched_barrier(0)
;     __device__ __forceinline__ void operator()(f32x4 (&acc)[2][2][4][2], const Unit& u, int wr, int wc, int fr, int fq) const {
;     ...
;         { const int lane = fr + 16 * fq, cL = u.pn * BM + wc * 32 + (lane < 32 ? lane : 96 + lane);
;           float vg = 0.f, vb = 0.f, vt = 0.f;
;           if (hasln) { vg = *(const GAS float*)(pg + cL); vb = *(const GAS float*)(pb + cL); }
; template <class Epi>
; __device__ __forceinline__ void gemm_phase(LAS unsigned char* lds, const Gemm g0, const StaticOrder& S, const Epi& E) {
;     ...
;             PG8_LDA(At, 1, 1); PG8_STAGE(PG8_SA(1, 0), a3, voffA);
;             PG8_BAR; PG8_WAIT_L(0); PG8_MMA(1, 0, At, B0); PG8_BAR; PG8_SCHED;
;             PG8_STAGE(PG8_SB(1, 1), b3 + hstep, voffB);
;             PG8_WAIT_V(6); PG8_BAR; PG8_MMA(1, 1, At, B1); PG8_BAR;
;         }
	s_waitcnt lgkmcnt(0)
	s_setprio 0
	s_waitcnt lgkmcnt(0)
	v_mfma_f32_16x16x32_f16 v[118:121], v[212:215], v[146:149], v[118:121]
	v_mfma_f32_16x16x32_f16 v[114:117], v[238:241], v[146:149], v[114:117]
	v_mfma_f32_16x16x32_f16 v[102:105], v[212:215], v[154:157], v[102:105]
	v_mfma_f32_16x16x32_f16 v[98:101], v[238:241], v[154:157], v[98:101]
	v_mfma_f32_16x16x32_f16 v[86:89], v[212:215], v[188:191], v[86:89]
	v_mfma_f32_16x16x32_f16 v[82:85], v[238:241], v[188:191], v[82:85]
	v_mfma_f32_16x16x32_f16 v[70:73], v[212:215], v[196:199], v[70:73]
	v_mfma_f32_16x16x32_f16 v[66:69], v[238:241], v[196:199], v[66:69]
	v_mfma_f32_16x16x32_f16 v[118:121], v[234:237], v[150:153], v[118:121]
	v_mfma_f32_16x16x32_f16 v[114:117], v[242:245], v[150:153], v[114:117]
	v_mfma_f32_16x16x32_f16 v[102:105], v[234:237], v[158:161], v[102:105]
	v_mfma_f32_16x16x32_f16 v[98:101], v[242:245], v[158:161], v[98:101]
	v_mfma_f32_16x16x32_f16 v[86:89], v[234:237], v[192:195], v[86:89]
	v_mfma_f32_16x16x32_f16 v[82:85], v[242:245], v[192:195], v[82:85]
	v_mfma_f32_16x16x32_f16 v[70:73], v[234:237], v[200:203], v[70:73]
	v_mfma_f32_16x16x32_f16 v[66:69], v[242:245], v[200:203], v[66:69]
	s_setprio 1
	s_mov_b32 m0, s28
	v_lshl_add_u64 v[162:163], v[170:171], 0, s[64:65]
	s_barrier
	ds_read_b128 v[146:149], v210 offset:49152
	ds_read_b128 v[150:153], v210 offset:50176
	ds_read_b128 v[154:157], v210 offset:51200
	ds_read_b128 v[158:161], v210 offset:52224
	ds_read_b128 v[188:191], v210 offset:53248
	ds_read_b128 v[192:195], v210 offset:54272
	ds_read_b128 v[196:199], v210 offset:55296
	ds_read_b128 v[200:203], v210 offset:56320
	global_load_lds_dwordx4 v[162:163], off
	v_lshl_add_u64 v[162:163], v[172:173], 0, s[64:65]
	s_mov_b32 m0, s29
	s_nop 0
	global_load_lds_dwordx4 v[162:163], off
	s_barrier
	s_waitcnt lgkmcnt(0)
	s_setprio 0
	s_waitcnt lgkmcnt(0)
	v_mfma_f32_16x16x32_f16 v[62:65], v[122:125], v[146:149], v[62:65]
	v_mfma_f32_16x16x32_f16 v[58:61], v[138:141], v[146:149], v[58:61]
	v_mfma_f32_16x16x32_f16 v[46:49], v[122:125], v[154:157], v[46:49]
	v_mfma_f32_16x16x32_f16 v[42:45], v[138:141], v[154:157], v[42:45]
	v_mfma_f32_16x16x32_f16 v[30:33], v[122:125], v[188:191], v[30:33]
	v_mfma_f32_16x16x32_f16 v[26:29], v[138:141], v[188:191], v[26:29]
	v_mfma_f32_16x16x32_f16 v[14:17], v[122:125], v[196:199], v[14:17]
	v_mfma_f32_16x16x32_f16 v[10:13], v[138:141], v[196:199], v[10:13]
	v_mfma_f32_16x16x32_f16 v[62:65], v[126:129], v[150:153], v[62:65]
	v_mfma_f32_16x16x32_f16 v[58:61], v[142:145], v[150:153], v[58:61]
	v_mfma_f32_16x16x32_f16 v[46:49], v[126:129], v[158:161], v[46:49]
	v_mfma_f32_16x16x32_f16 v[42:45], v[142:145], v[158:161], v[42:45]
	v_mfma_f32_16x16x32_f16 v[30:33], v[126:129], v[192:195], v[30:33]
	v_mfma_f32_16x16x32_f16 v[26:29], v[142:145], v[192:195], v[26:29]
	v_mfma_f32_16x16x32_f16 v[14:17], v[126:129], v[200:203], v[14:17]
	v_mfma_f32_16x16x32_f16 v[10:13], v[142:145], v[200:203], v[10:13]
	s_setprio 1
	s_barrier
	s_add_u32 s48, s48, 0x80080
	s_addc_u32 s49, s49, 0
	s_add_i32 s23, s50, s75
	v_lshl_add_u64 v[122:123], s[48:49], 0, v[178:179]
	s_mov_b32 m0, s23
	s_nop 0
	global_load_lds_dwordx4 v[122:123], off
	v_lshl_add_u64 v[122:123], s[48:49], 0, v[174:175]
	s_add_i32 m0, s23, 0x2000
	s_nop 0
	global_load_lds_dwordx4 v[122:123], off
	s_waitcnt vmcnt(6)
	s_barrier
	s_setprio 0
	v_mfma_f32_16x16x32_f16 v[54:57], v[212:215], v[146:149], v[54:57]
	v_mfma_f32_16x16x32_f16 v[50:53], v[238:241], v[146:149], v[50:53]
	v_mfma_f32_16x16x32_f16 v[38:41], v[212:215], v[154:157], v[38:41]
	v_mfma_f32_16x16x32_f16 v[34:37], v[238:241], v[154:157], v[34:37]
	v_mfma_f32_16x16x32_f16 v[22:25], v[212:215], v[188:191], v[22:25]
	v_mfma_f32_16x16x32_f16 v[18:21], v[238:241], v[188:191], v[18:21]
	v_mfma_f32_16x16x32_f16 v[6:9], v[212:215], v[196:199], v[6:9]
	v_mfma_f32_16x16x32_f16 v[2:5], v[238:241], v[196:199], v[2:5]
	v_mfma_f32_16x16x32_f16 v[54:57], v[234:237], v[150:153], v[54:57]
	v_mfma_f32_16x16x32_f16 v[50:53], v[242:245], v[150:153], v[50:53]
	v_mfma_f32_16x16x32_f16 v[38:41], v[234:237], v[158:161], v[38:41]
	v_mfma_f32_16x16x32_f16 v[34:37], v[242:245], v[158:161], v[34:37]
	v_mfma_f32_16x16x32_f16 v[22:25], v[234:237], v[192:195], v[22:25]
	v_mfma_f32_16x16x32_f16 v[18:21], v[242:245], v[192:195], v[18:21]
	v_mfma_f32_16x16x32_f16 v[6:9], v[234:237], v[200:203], v[6:9]
	v_mfma_f32_16x16x32_f16 v[2:5], v[242:245], v[200:203], v[2:5]
	s_setprio 1
	s_add_i32 s22, s22, 2
	s_add_u32 vcc_lo, vcc_lo, 0x100
	s_addc_u32 vcc_hi, vcc_hi, 0
	s_add_u32 s12, s12, 0x100
	s_addc_u32 s13, s13, 0
	s_cmp_gt_u32 s22, 29
	s_barrier
	s_cbranch_scc0 .LBB0_512
	s_lshl_b32 s12, s83, 8
	s_or_b32 s15, s12, s31
	v_add_u32_e32 v122, s15, v206
	v_cndmask_b32_e64 v124, 0, 1, s[44:45]
	v_ashrrev_i32_e32 v123, 31, v122
	v_mov_b32_e32 v196, 0
	v_cmp_ne_u32_e64 s[12:13], 1, v124
	s_andn2_b64 vcc, exec, s[44:45]
	v_mov_b32_e32 v124, 0
	v_mov_b32_e32 v125, 0
	s_cbranch_vccnz .LBB0_515
	v_lshlrev_b64 v[124:125], 2, v[122:123]
	v_lshl_add_u64 v[126:127], s[80:81], 0, v[124:125]
	v_lshl_add_u64 v[124:125], s[58:59], 0, v[124:125]
	global_load_dword v125, v[124:125], off
	s_nop 0
	global_load_dword v124, v[126:127], off

;     __device__ __forceinline__ void prefetch(const Unit& u, int wr, int wc, int lane) const { lnfold_prefetch(vl, stats, gW, bW, u, wr, wc, lane); }
;     __device__ __forceinline__ void prefetch(const Unit& u, int wr, int wc, int lane) const { lnfold_prefetch(vl, stats, gW, bW, u, wr, wc, lane); }
; #define PG8_STAGE(bufoff, gbase, voff) do { _Pragma("unroll") for (int _i = 0; _i < 2; ++_i) \
;         __builtin_amdgcn_global_load_lds((const unsigned*)((const char*)(gbase) + (voff)[_i]), (LAS unsigned*)(lds + (bufoff) + ldsw + _i * 8192), 16, 0, 0); } while (0)
; #define PG8_LDA(dst, b, h) do { _Pragma("unroll") for (int m = 0; m < 4; ++m) _Pragma("unroll") for (int k = 0; k < 2; ++k) dst[m][k] = *(const LAS f16x8*)(lds + PG8_SA(b, h) + aoff + m * 2048 + k * 1024); } while (0)
; #define PG8_LDB(dst, b, h) do { _Pragma("unroll") for (int n = 0; n < 2; ++n) _Pragma("unroll") for (int k = 0; k < 2; ++k) dst[n][k] = *(const LAS f16x8*)(lds + PG8_SB(b, h) + boff + n * 2048 + k * 1024); } while (0)
; #define PG8_WAIT_V(n) asm volatile("s_waitcnt vmcnt(" #n ")" ::: "memory")
; #define PG8_WAIT_L(n) asm volatile("s_waitcnt lgkmcnt(" #n ")" ::: "memory")
; #define PG8_BAR __builtin_amdgcn_s_barrier()
; template <class Epi>
; __device__ __forceinline__ void gemm_phase(LAS unsigned char* lds, const Gemm g0, const StaticOrder& S, const Epi& E) {
;     ...
;             const bool last = (t == nt - 2);
;             if (Epi::PREF && last) E.prefetch(cur, wr, wc, lane);
;             const char* a1 = cA + (size_t)(t + 1) * kstep;
;             const char* a2 = last ? nA : cA + (size_t)(t + 2) * kstep; const char* b2 = last ? nB : cB + (size_t)(t + 2) * kstep;
;             const char* a3 = a2 + kstep; const char* b3 = b2 + kstep;
;             PG8_LDB(B0, 0, 0); PG8_SCHED; PG8_LDA(At, 0, 0); PG8_STAGE(PG8_SA(1, 1), a1 + hstep, voffA);
;             PG8_WAIT_L(8); PG8_BAR; PG8_WAIT_L(0); PG8_MMA(0, 0, At, B0); PG8_BAR; PG8_SCHED;
;             PG8_LDB(B1, 0, 1); PG8_STAGE(PG8_SB(0, 0), b2, voffB);
;             PG8_BAR; PG8_WAIT_L(0); PG8_MMA(0, 1, At, B1); PG8_BAR;
;             PG8_LDA(At, 0, 1); PG8_STAGE(PG8_SA(0, 0), a2, voffA);
;             PG8_BAR; PG8_WAIT_L(0); PG8_MMA(1, 0, At, B0); PG8_BAR; PG8_SCHED;
;             PG8_STAGE(PG8_SB(0, 1), b2 + hstep, voffB);
;             PG8_WAIT_V(6); PG8_BAR; PG8_MMA(1, 1, At, B1); PG8_BAR;
.LBB0_620:
	s_add_u32 s58, s50, 0xfff80080
	s_addc_u32 s59, s51, -1
	s_and_b64 s[22:23], s[52:53], exec
	s_cselect_b32 s59, s37, s59
	s_cselect_b32 s58, s74, s58
	s_add_i32 s82, 0, 0x10000
	v_add_u32_e32 v68, s82, v189
	ds_read_b128 v[60:63], v68
	ds_read_b128 v[64:67], v68 offset:1024
	ds_read_b128 v[78:81], v68 offset:2048
	ds_read_b128 v[82:85], v68 offset:3072
	s_and_b64 s[22:23], s[52:53], exec
	s_cselect_b32 s53, s35, s25
	s_cselect_b32 s52, s75, s24
	v_lshl_add_u64 v[68:69], s[50:51], 0, v[184:185]
	s_add_i32 m0, s18, 0xc000
	ds_read_b128 v[86:89], v213
	ds_read_b128 v[90:93], v213 offset:1024
	ds_read_b128 v[194:197], v213 offset:2048
	ds_read_b128 v[234:237], v213 offset:3072
	ds_read_b128 v[238:241], v213 offset:4096
	ds_read_b128 v[242:245], v213 offset:5120
	ds_read_b128 v[246:249], v213 offset:6144
	ds_read_b128 v[226:229], v213 offset:7168
	global_load_lds_dwordx4 v[68:69], off
	v_lshl_add_u64 v[68:69], s[50:51], 0, v[182:183]
	s_add_i32 m0, s18, 0xe000
	s_nop 0
	global_load_lds_dwordx4 v[68:69], off
	s_waitcnt lgkmcnt(8)
	s_barrier
	s_waitcnt lgkmcnt(0)
	s_setprio 0
	s_waitcnt lgkmcnt(0)
	v_mfma_f32_16x16x32_f16 v[158:161], v[60:63], v[86:89], v[158:161]
	v_mfma_f32_16x16x32_f16 v[150:153], v[78:81], v[86:89], v[150:153]
	v_mfma_f32_16x16x32_f16 v[142:145], v[60:63], v[194:197], v[142:145]
	v_mfma_f32_16x16x32_f16 v[134:137], v[78:81], v[194:197], v[134:137]
	v_mfma_f32_16x16x32_f16 v[126:129], v[60:63], v[238:241], v[126:129]
	v_mfma_f32_16x16x32_f16 v[118:121], v[78:81], v[238:241], v[118:121]
	v_mfma_f32_16x16x32_f16 v[110:113], v[60:63], v[246:249], v[110:113]
	v_mfma_f32_16x16x32_f16 v[102:105], v[78:81], v[246:249], v[102:105]
	v_mfma_f32_16x16x32_f16 v[158:161], v[64:67], v[90:93], v[158:161]
	v_mfma_f32_16x16x32_f16 v[150:153], v[82:85], v[90:93], v[150:153]
	v_mfma_f32_16x16x32_f16 v[142:145], v[64:67], v[234:237], v[142:145]
	v_mfma_f32_16x16x32_f16 v[134:137], v[82:85], v[234:237], v[134:137]
	v_mfma_f32_16x16x32_f16 v[126:129], v[64:67], v[242:245], v[126:129]
	v_mfma_f32_16x16x32_f16 v[118:121], v[82:85], v[242:245], v[118:121]
	v_mfma_f32_16x16x32_f16 v[110:113], v[64:67], v[226:229], v[110:113]
	v_mfma_f32_16x16x32_f16 v[102:105], v[82:85], v[226:229], v[102:105]
	s_setprio 1
	s_barrier
	s_add_i32 s83, 0, 0x14000
	s_add_i32 s22, s82, s5
	v_add_u32_e32 v68, s83, v189
	v_lshl_add_u64 v[186:187], s[52:53], 0, v[178:179]
	s_mov_b32 m0, s22
	ds_read_b128 v[162:165], v68
	ds_read_b128 v[222:225], v68 offset:1024
	ds_read_b128 v[214:217], v68 offset:2048
	ds_read_b128 v[170:173], v68 offset:3072
	global_load_lds_dwordx4 v[186:187], off
	v_lshl_add_u64 v[190:191], s[52:53], 0, v[174:175]
	s_add_i32 m0, s22, 0x2000
	s_nop 0
	global_load_lds_dwordx4 v[190:191], off
	s_barrier
	s_waitcnt lgkmcnt(0)
	s_setprio 0
	s_waitcnt lgkmcnt(0)
	v_mfma_f32_16x16x32_f16 v[154:157], v[162:165], v[86:89], v[154:157]
	v_mfma_f32_16x16x32_f16 v[86:89], v[214:217], v[86:89], v[146:149]
	v_mfma_f32_16x16x32_f16 v[130:133], v[214:217], v[194:197], v[130:133]
	v_mfma_f32_16x16x32_f16 v[122:125], v[162:165], v[238:241], v[122:125]
	v_mfma_f32_16x16x32_f16 v[114:117], v[214:217], v[238:241], v[114:117]
	v_mfma_f32_16x16x32_f16 v[106:109], v[162:165], v[246:249], v[106:109]
	v_mfma_f32_16x16x32_f16 v[98:101], v[214:217], v[246:249], v[98:101]
	v_mfma_f32_16x16x32_f16 v[154:157], v[222:225], v[90:93], v[154:157]
	v_mfma_f32_16x16x32_f16 v[86:89], v[170:173], v[90:93], v[86:89]
	v_mfma_f32_16x16x32_f16 v[90:93], v[162:165], v[194:197], v[138:141]
	v_mfma_f32_16x16x32_f16 v[130:133], v[170:173], v[234:237], v[130:133]
	v_mfma_f32_16x16x32_f16 v[122:125], v[222:225], v[242:245], v[122:125]
	v_mfma_f32_16x16x32_f16 v[114:117], v[170:173], v[242:245], v[114:117]
	v_mfma_f32_16x16x32_f16 v[106:109], v[222:225], v[226:229], v[106:109]
	v_mfma_f32_16x16x32_f16 v[98:101], v[170:173], v[226:229], v[98:101]
	v_mfma_f32_16x16x32_f16 v[90:93], v[222:225], v[234:237], v[90:93]
	s_setprio 1
	s_mov_b32 m0, s18
	v_lshl_add_u64 v[198:199], s[58:59], 0, v[180:181]
	s_barrier
	ds_read_b128 v[138:141], v213 offset:16384
	ds_read_b128 v[146:149], v213 offset:17408
	ds_read_b128 v[194:197], v213 offset:18432
	ds_read_b128 v[226:229], v213 offset:19456
	ds_read_b128 v[234:237], v213 offset:20480
	ds_read_b128 v[238:241], v213 offset:21504
	ds_read_b128 v[242:245], v213 offset:22528
	ds_read_b128 v[246:249], v213 offset:23552
	global_load_lds_dwordx4 v[198:199], off
	v_lshl_add_u64 v[202:203], s[58:59], 0, v[176:177]
	s_mov_b32 m0, s19
	s_nop 0
	global_load_lds_dwordx4 v[202:203], off
	s_barrier
	s_waitcnt lgkmcnt(0)
	s_setprio 0
	s_waitcnt lgkmcnt(0)
	v_mfma_f32_16x16x32_f16 v[94:97], v[60:63], v[138:141], v[94:97]
	v_mfma_f32_16x16x32_f16 v[68:71], v[78:81], v[138:141], v[70:73]
	v_mfma_f32_16x16x32_f16 v[46:49], v[60:63], v[194:197], v[46:49]
	v_mfma_f32_16x16x32_f16 v[38:41], v[78:81], v[194:197], v[38:41]
	v_mfma_f32_16x16x32_f16 v[30:33], v[60:63], v[234:237], v[30:33]
	v_mfma_f32_16x16x32_f16 v[22:25], v[78:81], v[234:237], v[22:25]
	v_mfma_f32_16x16x32_f16 v[14:17], v[60:63], v[242:245], v[14:17]
	v_mfma_f32_16x16x32_f16 v[6:9], v[78:81], v[242:245], v[6:9]
	v_mfma_f32_16x16x32_f16 v[94:97], v[64:67], v[146:149], v[94:97]
	v_mfma_f32_16x16x32_f16 v[68:71], v[82:85], v[146:149], v[68:71]
	v_mfma_f32_16x16x32_f16 v[46:49], v[64:67], v[226:229], v[46:49]
	v_mfma_f32_16x16x32_f16 v[38:41], v[82:85], v[226:229], v[38:41]
	v_mfma_f32_16x16x32_f16 v[30:33], v[64:67], v[238:241], v[30:33]
	v_mfma_f32_16x16x32_f16 v[22:25], v[82:85], v[238:241], v[22:25]
	v_mfma_f32_16x16x32_f16 v[14:17], v[64:67], v[246:249], v[14:17]
	v_mfma_f32_16x16x32_f16 v[6:9], v[82:85], v[246:249], v[6:9]
	s_setprio 1
	s_barrier
; #define PG8_STAGE(bufoff, gbase, voff) do { _Pragma("unroll") for (int _i = 0; _i < 2; ++_i) \
;         __builtin_amdgcn_global_load_lds((const unsigned*)((const char*)(gbase) + (voff)[_i]), (LAS unsigned*)(lds + (bufoff) + ldsw + _i * 8192), 16, 0, 0); } while (0)
; #define PG8_LDA(dst, b, h) do { _Pragma("unroll") for (int m = 0; m < 4; ++m) _Pragma("unroll") for (int k = 0; k < 2; ++k) dst[m][k] = *(const LAS f16x8*)(lds + PG8_SA(b, h) + aoff + m * 2048 + k * 1024); } while (0)
; #define PG8_LDB(dst, b, h) do { _Pragma("unroll") for (int n = 0; n < 2; ++n) _Pragma("unroll") for (int k = 0; k < 2; ++k) dst[n][k] = *(const LAS f16x8*)(lds + PG8_SB(b, h) + boff + n * 2048 + k * 1024); } while (0)
; #define PG8_MMA(ai, bj, At, Bt) do { __builtin_amdgcn_s_setprio(1); _Pragma("unroll") for (int m = 0; m < 4; ++m) _Pragma("unroll") for (int n = 0; n < 2; ++n) _Pragma("unroll") for (int k = 0; k < 2; ++k) \
;         acc[ai][bj][m][n] = __builtin_amdgcn_mfma_f32_16x16x32_f16(Bt[n][k], At[m][k], acc[ai][bj][m][n], 0, 0, 0); __builtin_amdgcn_s_setprio(0); } while (0)
; #define PG8_WAIT_V(n) asm volatile("s_waitcnt vmcnt(" #n ")" ::: "memory")
; #define PG8_WAIT_L(n) asm volatile("s_waitcnt lgkmcnt(" #n ")" ::: "memory")
; #define PG8_BAR __builtin_amdgcn_s_barrier()
; #define PG8_SCHED __builtin_amdgcn_sched_barrier(0)
; template <class Epi>
; __device__ __forceinline__ void gemm_phase(LAS unsigned char* lds, const Gemm g0, const StaticOrder& S, const Epi& E) {
;     ...
;             PG8_WAIT_V(6); PG8_BAR; PG8_MMA(1, 1, At, B1); PG8_BAR;
;             PG8_LDB(B0, 1, 0); PG8_SCHED; PG8_LDA(At, 1, 0); PG8_STAGE(PG8_SA(0, 1), a2 + hstep, voffA);
;             PG8_WAIT_L(8); PG8_BAR; PG8_WAIT_L(0); PG8_MMA(0, 0, At, B0); PG8_BAR; PG8_SCHED;
;             PG8_LDB(B1, 1, 1); PG8_STAGE(PG8_SB(1, 0), b3, voffB);
;             PG8_BAR; PG8_WAIT_L(0); PG8_MMA(0, 1, At, B1); PG8_BAR;
	s_add_u32 s22, s52, 0x80000
	s_addc_u32 s23, s53, 0
	s_add_i32 s82, s83, s5
	v_lshl_add_u64 v[60:61], s[22:23], 0, v[178:179]
	s_mov_b32 m0, s82
	s_nop 0
	global_load_lds_dwordx4 v[60:61], off
	v_lshl_add_u64 v[60:61], s[22:23], 0, v[174:175]
	s_add_i32 m0, s82, 0x2000
	s_nop 0
	global_load_lds_dwordx4 v[60:61], off
	s_waitcnt vmcnt(6)
	s_barrier
	s_setprio 0
	v_mfma_f32_16x16x32_f16 v[50:53], v[214:217], v[138:141], v[50:53]
	v_mfma_f32_16x16x32_f16 v[42:45], v[162:165], v[194:197], v[42:45]
	v_mfma_f32_16x16x32_f16 v[34:37], v[214:217], v[194:197], v[34:37]
	v_mfma_f32_16x16x32_f16 v[26:29], v[162:165], v[234:237], v[26:29]
	v_mfma_f32_16x16x32_f16 v[18:21], v[214:217], v[234:237], v[18:21]
	v_mfma_f32_16x16x32_f16 v[10:13], v[162:165], v[242:245], v[10:13]
	v_mfma_f32_16x16x32_f16 v[2:5], v[214:217], v[242:245], v[2:5]
	v_mfma_f32_16x16x32_f16 v[60:63], v[162:165], v[138:141], v[74:77]
	v_mfma_f32_16x16x32_f16 v[50:53], v[170:173], v[146:149], v[50:53]
	v_mfma_f32_16x16x32_f16 v[42:45], v[222:225], v[226:229], v[42:45]
	v_mfma_f32_16x16x32_f16 v[34:37], v[170:173], v[226:229], v[34:37]
	v_mfma_f32_16x16x32_f16 v[26:29], v[222:225], v[238:241], v[26:29]
	v_mfma_f32_16x16x32_f16 v[18:21], v[170:173], v[238:241], v[18:21]
	v_mfma_f32_16x16x32_f16 v[10:13], v[222:225], v[246:249], v[10:13]
	v_mfma_f32_16x16x32_f16 v[2:5], v[170:173], v[246:249], v[2:5]
	v_mfma_f32_16x16x32_f16 v[60:63], v[222:225], v[146:149], v[60:63]
	s_setprio 1
	s_add_i32 s82, 0, 0x18000
	v_add_u32_e32 v72, s82, v189
	s_barrier
	ds_read_b128 v[64:67], v72
	ds_read_b128 v[74:77], v72 offset:1024
	ds_read_b128 v[78:81], v72 offset:2048
	ds_read_b128 v[82:85], v72 offset:3072
	s_add_u32 s22, s58, 0x80000
	s_addc_u32 s23, s59, 0
	s_mov_b32 m0, s28
	v_lshl_add_u64 v[72:73], s[22:23], 0, v[180:181]
	ds_read_b128 v[138:141], v213 offset:32768
	ds_read_b128 v[146:149], v213 offset:33792
	ds_read_b128 v[162:165], v213 offset:34816
	ds_read_b128 v[170:173], v213 offset:35840
	ds_read_b128 v[194:197], v213 offset:36864
	ds_read_b128 v[214:217], v213 offset:37888
	ds_read_b128 v[222:225], v213 offset:38912
	ds_read_b128 v[226:229], v213 offset:39936
	global_load_lds_dwordx4 v[72:73], off
	v_lshl_add_u64 v[72:73], s[22:23], 0, v[176:177]
	s_mov_b32 m0, s29
	s_nop 0
	global_load_lds_dwordx4 v[72:73], off
	s_waitcnt lgkmcnt(8)
	s_barrier
	s_waitcnt lgkmcnt(0)
	s_setprio 0
	s_waitcnt lgkmcnt(0)
	v_mfma_f32_16x16x32_f16 v[158:161], v[64:67], v[138:141], v[158:161]
	v_mfma_f32_16x16x32_f16 v[150:153], v[78:81], v[138:141], v[150:153]
	v_mfma_f32_16x16x32_f16 v[142:145], v[64:67], v[162:165], v[142:145]
	v_mfma_f32_16x16x32_f16 v[134:137], v[78:81], v[162:165], v[134:137]
	v_mfma_f32_16x16x32_f16 v[126:129], v[64:67], v[194:197], v[126:129]
	v_mfma_f32_16x16x32_f16 v[118:121], v[78:81], v[194:197], v[118:121]
	v_mfma_f32_16x16x32_f16 v[110:113], v[64:67], v[222:225], v[110:113]
	v_mfma_f32_16x16x32_f16 v[102:105], v[78:81], v[222:225], v[102:105]
	v_mfma_f32_16x16x32_f16 v[158:161], v[74:77], v[146:149], v[158:161]
	v_mfma_f32_16x16x32_f16 v[150:153], v[82:85], v[146:149], v[150:153]
	v_mfma_f32_16x16x32_f16 v[142:145], v[74:77], v[170:173], v[142:145]
	v_mfma_f32_16x16x32_f16 v[134:137], v[82:85], v[170:173], v[134:137]
	v_mfma_f32_16x16x32_f16 v[126:129], v[74:77], v[214:217], v[126:129]
	v_mfma_f32_16x16x32_f16 v[118:121], v[82:85], v[214:217], v[118:121]
	v_mfma_f32_16x16x32_f16 v[110:113], v[74:77], v[226:229], v[110:113]
	v_mfma_f32_16x16x32_f16 v[102:105], v[82:85], v[226:229], v[102:105]
	s_setprio 1
	s_barrier
	s_add_i32 s58, 0, 0x1c000
	v_add_u32_e32 v72, s58, v189
	s_add_i32 s22, s82, s5
	ds_read_b128 v[234:237], v72
	ds_read_b128 v[238:241], v72 offset:1024
	ds_read_b128 v[242:245], v72 offset:2048
	ds_read_b128 v[246:249], v72 offset:3072
	v_lshl_add_u64 v[72:73], v[186:187], 0, s[64:65]
	s_mov_b32 m0, s22
	s_nop 0
	global_load_lds_dwordx4 v[72:73], off
	v_lshl_add_u64 v[72:73], v[190:191], 0, s[64:65]
	s_add_i32 m0, s22, 0x2000
	s_nop 0
	global_load_lds_dwordx4 v[72:73], off
	s_barrier
; #define PG8_STAGE(bufoff, gbase, voff) do { _Pragma("unroll") for (int _i = 0; _i < 2; ++_i) \
;         __builtin_amdgcn_global_load_lds((const unsigned*)((const char*)(gbase) + (voff)[_i]), (LAS unsigned*)(lds + (bufoff) + ldsw + _i * 8192), 16, 0, 0); } while (0)
; #define PG8_LDA(dst, b, h) do { _Pragma("unroll") for (int m = 0; m < 4; ++m) _Pragma("unroll") for (int k = 0; k < 2; ++k) dst[m][k] = *(const LAS f16x8*)(lds + PG8_SA(b, h) + aoff + m * 2048 + k * 1024); } while (0)
; #define PG8_MMA(ai, bj, At, Bt) do { __builtin_amdgcn_s_setprio(1); _Pragma("unroll") for (int m = 0; m < 4; ++m) _Pragma("unroll") for (int n = 0; n < 2; ++n) _Pragma("unroll") for (int k = 0; k < 2; ++k) \
;         acc[ai][bj][m][n] = __builtin_amdgcn_mfma_f32_16x16x32_f16(Bt[n][k], At[m][k], acc[ai][bj][m][n], 0, 0, 0); __builtin_amdgcn_s_setprio(0); } while (0)
; #define PG8_WAIT_V(n) asm volatile("s_waitcnt vmcnt(" #n ")" ::: "memory")
; #define PG8_WAIT_L(n) asm volatile("s_waitcnt lgkmcnt(" #n ")" ::: "memory")
; #define PG8_BAR __builtin_amdgcn_s_barrier()
; #define PG8_SCHED __builtin_amdgcn_sched_barrier(0)
; template <class Epi>
; __device__ __forceinline__ void gemm_phase(LAS unsigned char* lds, const Gemm g0, const StaticOrder& S, const Epi& E) {
;     ...
;             PG8_BAR; PG8_WAIT_L(0); PG8_MMA(0, 1, At, B1); PG8_BAR;
;             PG8_LDA(At, 1, 1); PG8_STAGE(PG8_SA(1, 0), a3, voffA);
;             PG8_BAR; PG8_WAIT_L(0); PG8_MMA(1, 0, At, B0); PG8_BAR; PG8_SCHED;
;             PG8_STAGE(PG8_SB(1, 1), b3 + hstep, voffB);
;             PG8_WAIT_V(6); PG8_BAR; PG8_MMA(1, 1, At, B1); PG8_BAR;
;         }
	s_waitcnt lgkmcnt(0)
	s_setprio 0
	s_waitcnt lgkmcnt(0)
	v_mfma_f32_16x16x32_f16 v[154:157], v[234:237], v[138:141], v[154:157]
	v_mfma_f32_16x16x32_f16 v[86:89], v[242:245], v[138:141], v[86:89]
	v_mfma_f32_16x16x32_f16 v[154:157], v[238:241], v[146:149], v[154:157]
	v_mfma_f32_16x16x32_f16 v[146:149], v[246:249], v[146:149], v[86:89]
	v_mfma_f32_16x16x32_f16 v[86:89], v[234:237], v[162:165], v[90:93]
	v_mfma_f32_16x16x32_f16 v[138:141], v[238:241], v[170:173], v[86:89]
	v_mfma_f32_16x16x32_f16 v[86:89], v[242:245], v[162:165], v[130:133]
	v_mfma_f32_16x16x32_f16 v[130:133], v[246:249], v[170:173], v[86:89]
	v_mfma_f32_16x16x32_f16 v[86:89], v[234:237], v[194:197], v[122:125]
	v_mfma_f32_16x16x32_f16 v[122:125], v[238:241], v[214:217], v[86:89]
	v_mfma_f32_16x16x32_f16 v[86:89], v[242:245], v[194:197], v[114:117]
	v_mfma_f32_16x16x32_f16 v[114:117], v[246:249], v[214:217], v[86:89]
	v_mfma_f32_16x16x32_f16 v[86:89], v[234:237], v[222:225], v[106:109]
	v_mfma_f32_16x16x32_f16 v[106:109], v[238:241], v[226:229], v[86:89]
	v_mfma_f32_16x16x32_f16 v[86:89], v[242:245], v[222:225], v[98:101]
	v_mfma_f32_16x16x32_f16 v[98:101], v[246:249], v[226:229], v[86:89]
	s_setprio 1
	s_mov_b32 m0, s31
	v_lshl_add_u64 v[72:73], v[198:199], 0, s[64:65]
	s_barrier
	s_nop 2
	ds_read_b128 v[86:89], v213 offset:49152
	ds_read_b128 v[90:93], v213 offset:50176
	ds_read_b128 v[162:165], v213 offset:51200
	ds_read_b128 v[170:173], v213 offset:52224
	ds_read_b128 v[194:197], v213 offset:53248
	ds_read_b128 v[214:217], v213 offset:54272
	ds_read_b128 v[222:225], v213 offset:55296
	ds_read_b128 v[226:229], v213 offset:56320
	global_load_lds_dwordx4 v[72:73], off
	v_lshl_add_u64 v[72:73], v[202:203], 0, s[64:65]
	s_mov_b32 m0, s61
	s_nop 0
	global_load_lds_dwordx4 v[72:73], off
	s_barrier
	s_waitcnt lgkmcnt(0)
	s_setprio 0
	s_waitcnt lgkmcnt(0)
	v_mfma_f32_16x16x32_f16 v[94:97], v[64:67], v[86:89], v[94:97]
	v_mfma_f32_16x16x32_f16 v[68:71], v[78:81], v[86:89], v[68:71]
	v_mfma_f32_16x16x32_f16 v[46:49], v[64:67], v[162:165], v[46:49]
	v_mfma_f32_16x16x32_f16 v[38:41], v[78:81], v[162:165], v[38:41]
	v_mfma_f32_16x16x32_f16 v[30:33], v[64:67], v[194:197], v[30:33]
	v_mfma_f32_16x16x32_f16 v[22:25], v[78:81], v[194:197], v[22:25]
	v_mfma_f32_16x16x32_f16 v[14:17], v[64:67], v[222:225], v[14:17]
	v_mfma_f32_16x16x32_f16 v[6:9], v[78:81], v[222:225], v[6:9]
	v_mfma_f32_16x16x32_f16 v[94:97], v[74:77], v[90:93], v[94:97]
	v_mfma_f32_16x16x32_f16 v[70:73], v[82:85], v[90:93], v[68:71]
	v_mfma_f32_16x16x32_f16 v[46:49], v[74:77], v[170:173], v[46:49]
	v_mfma_f32_16x16x32_f16 v[38:41], v[82:85], v[170:173], v[38:41]
	v_mfma_f32_16x16x32_f16 v[30:33], v[74:77], v[214:217], v[30:33]
	v_mfma_f32_16x16x32_f16 v[22:25], v[82:85], v[214:217], v[22:25]
	v_mfma_f32_16x16x32_f16 v[14:17], v[74:77], v[226:229], v[14:17]
	v_mfma_f32_16x16x32_f16 v[6:9], v[82:85], v[226:229], v[6:9]
	s_setprio 1
	s_barrier
	s_add_u32 s22, s52, 0x80080
	s_addc_u32 s23, s53, 0
	s_add_i32 s52, s58, s5
	v_lshl_add_u64 v[64:65], s[22:23], 0, v[178:179]
	s_mov_b32 m0, s52
	s_nop 0
	global_load_lds_dwordx4 v[64:65], off
	v_lshl_add_u64 v[64:65], s[22:23], 0, v[174:175]
	s_add_i32 m0, s52, 0x2000
	s_nop 0
	global_load_lds_dwordx4 v[64:65], off
	s_waitcnt vmcnt(6)
	s_barrier
	s_setprio 0
	v_mfma_f32_16x16x32_f16 v[60:63], v[234:237], v[86:89], v[60:63]
	v_mfma_f32_16x16x32_f16 v[50:53], v[242:245], v[86:89], v[50:53]
	v_mfma_f32_16x16x32_f16 v[42:45], v[234:237], v[162:165], v[42:45]
	v_mfma_f32_16x16x32_f16 v[34:37], v[242:245], v[162:165], v[34:37]
	v_mfma_f32_16x16x32_f16 v[26:29], v[234:237], v[194:197], v[26:29]
	v_mfma_f32_16x16x32_f16 v[18:21], v[242:245], v[194:197], v[18:21]
	v_mfma_f32_16x16x32_f16 v[10:13], v[234:237], v[222:225], v[10:13]
	v_mfma_f32_16x16x32_f16 v[2:5], v[242:245], v[222:225], v[2:5]
	v_mfma_f32_16x16x32_f16 v[74:77], v[238:241], v[90:93], v[60:63]
	v_mfma_f32_16x16x32_f16 v[50:53], v[246:249], v[90:93], v[50:53]
	v_mfma_f32_16x16x32_f16 v[42:45], v[238:241], v[170:173], v[42:45]
	v_mfma_f32_16x16x32_f16 v[34:37], v[246:249], v[170:173], v[34:37]
	v_mfma_f32_16x16x32_f16 v[26:29], v[238:241], v[214:217], v[26:29]
	v_mfma_f32_16x16x32_f16 v[18:21], v[246:249], v[214:217], v[18:21]
	v_mfma_f32_16x16x32_f16 v[10:13], v[238:241], v[226:229], v[10:13]
	v_mfma_f32_16x16x32_f16 v[2:5], v[246:249], v[226:229], v[2:5]
	s_setprio 1
	s_add_i32 s81, s81, 2
	s_add_u32 s24, s24, 0x100
	s_addc_u32 s25, s25, 0
	s_add_u32 s50, s50, 0x100
	s_addc_u32 s51, s51, 0
	s_cmp_gt_u32 s81, 29
	s_barrier
	s_cbranch_scc1 .LBB0_616

;     __device__ __forceinline__ void prefetch(const Unit& u, int wr, int wc, int lane) const { lnfold_prefetch(vl, stats, gW, bW, u, wr, wc, lane); }
;     __device__ __forceinline__ void prefetch(const Unit& u, int wr, int wc, int lane) const { lnfold_prefetch(vl, stats, gW, bW, u, wr, wc, lane); }
; #define PG8_STAGE(bufoff, gbase, voff) do { _Pragma("unroll") for (int _i = 0; _i < 2; ++_i) \
;         __builtin_amdgcn_global_load_lds((const unsigned*)((const char*)(gbase) + (voff)[_i]), (LAS unsigned*)(lds + (bufoff) + ldsw + _i * 8192), 16, 0, 0); } while (0)
; #define PG8_LDA(dst, b, h) do { _Pragma("unroll") for (int m = 0; m < 4; ++m) _Pragma("unroll") for (int k = 0; k < 2; ++k) dst[m][k] = *(const LAS f16x8*)(lds + PG8_SA(b, h) + aoff + m * 2048 + k * 1024); } while (0)
; #define PG8_LDB(dst, b, h) do { _Pragma("unroll") for (int n = 0; n < 2; ++n) _Pragma("unroll") for (int k = 0; k < 2; ++k) dst[n][k] = *(const LAS f16x8*)(lds + PG8_SB(b, h) + boff + n * 2048 + k * 1024); } while (0)
; #define PG8_MMA(ai, bj, At, Bt) do { __builtin_amdgcn_s_setprio(1); _Pragma("unroll") for (int m = 0; m < 4; ++m) _Pragma("unroll") for (int n = 0; n < 2; ++n) _Pragma("unroll") for (int k = 0; k < 2; ++k) \
;         acc[ai][bj][m][n] = __builtin_amdgcn_mfma_f32_16x16x32_f16(Bt[n][k], At[m][k], acc[ai][bj][m][n], 0, 0, 0); __builtin_amdgcn_s_setprio(0); } while (0)
; template <class Epi>
; __device__ __forceinline__ void gemm_phase(LAS unsigned char* lds, const Gemm g0, const StaticOrder& S, const Epi& E) {
;     ...
;             const bool last = (t == nt - 2);
;             if (Epi::PREF && last) E.prefetch(cur, wr, wc, lane);
;             const char* a1 = cA + (size_t)(t + 1) * kstep;
;             const char* a2 = last ? nA : cA + (size_t)(t + 2) * kstep; const char* b2 = last ? nB : cB + (size_t)(t + 2) * kstep;
;             const char* a3 = a2 + kstep; const char* b3 = b2 + kstep;
;             PG8_LDB(B0, 0, 0); PG8_SCHED; PG8_LDA(At, 0, 0); PG8_STAGE(PG8_SA(1, 1), a1 + hstep, voffA);
;             PG8_WAIT_L(8); PG8_BAR; PG8_WAIT_L(0); PG8_MMA(0, 0, At, B0); PG8_BAR; PG8_SCHED;
;             PG8_LDB(B1, 0, 1); PG8_STAGE(PG8_SB(0, 0), b2, voffB);
;             PG8_BAR; PG8_WAIT_L(0); PG8_MMA(0, 1, At, B1); PG8_BAR;
;             PG8_LDA(At, 0, 1); PG8_STAGE(PG8_SA(0, 0), a2, voffA);
;             PG8_BAR; PG8_WAIT_L(0); PG8_MMA(1, 0, At, B0); PG8_BAR; PG8_SCHED;
.LBB0_672:
	s_add_u32 s10, s12, 0x100
	s_addc_u32 s11, s13, 0
	s_add_i32 s23, 0, 0x10000
	v_add_u32_e32 v142, s23, v203
	ds_read_b128 v[130:133], v142
	ds_read_b128 v[134:137], v142 offset:1024
	ds_read_b128 v[138:141], v142 offset:2048
	ds_read_b128 v[142:145], v142 offset:3072
	s_cmpk_eq_i32 s22, 0x54
	s_cselect_b32 s81, s1, s11
	s_cselect_b32 s80, s0, s10
	s_cselect_b32 s63, s59, s25
	s_cselect_b32 s62, s58, s24
	v_lshl_add_u64 v[196:197], s[12:13], 0, v[182:183]
	s_add_i32 m0, s28, 0xc000
	ds_read_b128 v[146:149], v208
	ds_read_b128 v[150:153], v208 offset:1024
	ds_read_b128 v[154:157], v208 offset:2048
	ds_read_b128 v[162:165], v208 offset:3072
	ds_read_b128 v[170:173], v208 offset:4096
	ds_read_b128 v[184:187], v208 offset:5120
	ds_read_b128 v[188:191], v208 offset:6144
	ds_read_b128 v[192:195], v208 offset:7168
	global_load_lds_dwordx4 v[196:197], off
	v_lshl_add_u64 v[196:197], s[12:13], 0, v[180:181]
	s_add_i32 m0, s28, 0xe000
	s_nop 0
	global_load_lds_dwordx4 v[196:197], off
	s_waitcnt lgkmcnt(8)
	s_barrier
	s_waitcnt lgkmcnt(0)
	s_setprio 0
	s_waitcnt lgkmcnt(0)
	v_mfma_f32_16x16x32_f16 v[126:129], v[130:133], v[146:149], v[126:129]
	v_mfma_f32_16x16x32_f16 v[122:125], v[138:141], v[146:149], v[122:125]
	v_mfma_f32_16x16x32_f16 v[110:113], v[130:133], v[154:157], v[110:113]
	v_mfma_f32_16x16x32_f16 v[106:109], v[138:141], v[154:157], v[106:109]
	v_mfma_f32_16x16x32_f16 v[94:97], v[130:133], v[170:173], v[94:97]
	v_mfma_f32_16x16x32_f16 v[90:93], v[138:141], v[170:173], v[90:93]
	v_mfma_f32_16x16x32_f16 v[78:81], v[130:133], v[188:191], v[78:81]
	v_mfma_f32_16x16x32_f16 v[74:77], v[138:141], v[188:191], v[74:77]
	v_mfma_f32_16x16x32_f16 v[126:129], v[134:137], v[150:153], v[126:129]
	v_mfma_f32_16x16x32_f16 v[122:125], v[142:145], v[150:153], v[122:125]
	v_mfma_f32_16x16x32_f16 v[110:113], v[134:137], v[162:165], v[110:113]
	v_mfma_f32_16x16x32_f16 v[106:109], v[142:145], v[162:165], v[106:109]
	v_mfma_f32_16x16x32_f16 v[94:97], v[134:137], v[184:187], v[94:97]
	v_mfma_f32_16x16x32_f16 v[90:93], v[142:145], v[184:187], v[90:93]
	v_mfma_f32_16x16x32_f16 v[78:81], v[134:137], v[192:195], v[78:81]
	v_mfma_f32_16x16x32_f16 v[74:77], v[142:145], v[192:195], v[74:77]
	s_setprio 1
	s_barrier
	s_add_i32 s90, 0, 0x14000
	v_add_u32_e32 v200, s90, v203
	s_add_i32 s12, s23, s19
	ds_read_b128 v[196:199], v200
	ds_read_b128 v[210:213], v200 offset:1024
	ds_read_b128 v[214:217], v200 offset:2048
	ds_read_b128 v[222:225], v200 offset:3072
	v_lshl_add_u64 v[200:201], s[62:63], 0, v[174:175]
	s_mov_b32 m0, s12
	v_lshl_add_u64 v[218:219], s[62:63], 0, v[158:159]
	global_load_lds_dwordx4 v[200:201], off
	s_add_i32 m0, s12, 0x2000
	s_nop 0
	global_load_lds_dwordx4 v[218:219], off
	s_barrier
	s_waitcnt lgkmcnt(0)
	s_setprio 0
	s_waitcnt lgkmcnt(0)
	v_mfma_f32_16x16x32_f16 v[118:121], v[196:199], v[146:149], v[118:121]
	v_mfma_f32_16x16x32_f16 v[114:117], v[214:217], v[146:149], v[114:117]
	v_mfma_f32_16x16x32_f16 v[102:105], v[196:199], v[154:157], v[102:105]
	v_mfma_f32_16x16x32_f16 v[98:101], v[214:217], v[154:157], v[98:101]
	v_mfma_f32_16x16x32_f16 v[86:89], v[196:199], v[170:173], v[86:89]
	v_mfma_f32_16x16x32_f16 v[82:85], v[214:217], v[170:173], v[82:85]
	v_mfma_f32_16x16x32_f16 v[70:73], v[196:199], v[188:191], v[70:73]
	v_mfma_f32_16x16x32_f16 v[66:69], v[214:217], v[188:191], v[66:69]
	v_mfma_f32_16x16x32_f16 v[118:121], v[210:213], v[150:153], v[118:121]
	v_mfma_f32_16x16x32_f16 v[114:117], v[222:225], v[150:153], v[114:117]
	v_mfma_f32_16x16x32_f16 v[102:105], v[210:213], v[162:165], v[102:105]
	v_mfma_f32_16x16x32_f16 v[98:101], v[222:225], v[162:165], v[98:101]
	v_mfma_f32_16x16x32_f16 v[86:89], v[210:213], v[184:187], v[86:89]
	v_mfma_f32_16x16x32_f16 v[82:85], v[222:225], v[184:187], v[82:85]
	v_mfma_f32_16x16x32_f16 v[70:73], v[210:213], v[192:195], v[70:73]
	v_mfma_f32_16x16x32_f16 v[66:69], v[222:225], v[192:195], v[66:69]
	s_setprio 1
	s_mov_b32 m0, s28
	v_lshl_add_u64 v[226:227], s[80:81], 0, v[176:177]
	s_barrier
	ds_read_b128 v[146:149], v208 offset:16384
	ds_read_b128 v[150:153], v208 offset:17408
	ds_read_b128 v[154:157], v208 offset:18432
	ds_read_b128 v[162:165], v208 offset:19456
	ds_read_b128 v[170:173], v208 offset:20480
	ds_read_b128 v[184:187], v208 offset:21504
	ds_read_b128 v[188:191], v208 offset:22528
	ds_read_b128 v[192:195], v208 offset:23552
	global_load_lds_dwordx4 v[226:227], off
	v_lshl_add_u64 v[228:229], s[80:81], 0, v[160:161]
	s_mov_b32 m0, s29
	s_nop 0
	global_load_lds_dwordx4 v[228:229], off
	s_barrier
	s_waitcnt lgkmcnt(0)
	s_setprio 0
	s_waitcnt lgkmcnt(0)
	v_mfma_f32_16x16x32_f16 v[62:65], v[130:133], v[146:149], v[62:65]
	v_mfma_f32_16x16x32_f16 v[58:61], v[138:141], v[146:149], v[58:61]
	v_mfma_f32_16x16x32_f16 v[46:49], v[130:133], v[154:157], v[46:49]
	v_mfma_f32_16x16x32_f16 v[42:45], v[138:141], v[154:157], v[42:45]
	v_mfma_f32_16x16x32_f16 v[30:33], v[130:133], v[170:173], v[30:33]
	v_mfma_f32_16x16x32_f16 v[26:29], v[138:141], v[170:173], v[26:29]
	v_mfma_f32_16x16x32_f16 v[14:17], v[130:133], v[188:191], v[14:17]
	v_mfma_f32_16x16x32_f16 v[10:13], v[138:141], v[188:191], v[10:13]
	v_mfma_f32_16x16x32_f16 v[62:65], v[134:137], v[150:153], v[62:65]
	v_mfma_f32_16x16x32_f16 v[58:61], v[142:145], v[150:153], v[58:61]
	v_mfma_f32_16x16x32_f16 v[46:49], v[134:137], v[162:165], v[46:49]
	v_mfma_f32_16x16x32_f16 v[42:45], v[142:145], v[162:165], v[42:45]
	v_mfma_f32_16x16x32_f16 v[30:33], v[134:137], v[184:187], v[30:33]
	v_mfma_f32_16x16x32_f16 v[26:29], v[142:145], v[184:187], v[26:29]
	v_mfma_f32_16x16x32_f16 v[14:17], v[134:137], v[192:195], v[14:17]
	v_mfma_f32_16x16x32_f16 v[10:13], v[142:145], v[192:195], v[10:13]
	s_setprio 1
	s_barrier
; #define PG8_STAGE(bufoff, gbase, voff) do { _Pragma("unroll") for (int _i = 0; _i < 2; ++_i) \
;         __builtin_amdgcn_global_load_lds((const unsigned*)((const char*)(gbase) + (voff)[_i]), (LAS unsigned*)(lds + (bufoff) + ldsw + _i * 8192), 16, 0, 0); } while (0)
; #define PG8_LDA(dst, b, h) do { _Pragma("unroll") for (int m = 0; m < 4; ++m) _Pragma("unroll") for (int k = 0; k < 2; ++k) dst[m][k] = *(const LAS f16x8*)(lds + PG8_SA(b, h) + aoff + m * 2048 + k * 1024); } while (0)
; #define PG8_LDB(dst, b, h) do { _Pragma("unroll") for (int n = 0; n < 2; ++n) _Pragma("unroll") for (int k = 0; k < 2; ++k) dst[n][k] = *(const LAS f16x8*)(lds + PG8_SB(b, h) + boff + n * 2048 + k * 1024); } while (0)
; #define PG8_MMA(ai, bj, At, Bt) do { __builtin_amdgcn_s_setprio(1); _Pragma("unroll") for (int m = 0; m < 4; ++m) _Pragma("unroll") for (int n = 0; n < 2; ++n) _Pragma("unroll") for (int k = 0; k < 2; ++k) \
;         acc[ai][bj][m][n] = __builtin_amdgcn_mfma_f32_16x16x32_f16(Bt[n][k], At[m][k], acc[ai][bj][m][n], 0, 0, 0); __builtin_amdgcn_s_setprio(0); } while (0)
; #define PG8_WAIT_V(n) asm volatile("s_waitcnt vmcnt(" #n ")" ::: "memory")
; #define PG8_WAIT_L(n) asm volatile("s_waitcnt lgkmcnt(" #n ")" ::: "memory")
; #define PG8_BAR __builtin_amdgcn_s_barrier()
; #define PG8_SCHED __builtin_amdgcn_sched_barrier(0)
; template <class Epi>
; __device__ __forceinline__ void gemm_phase(LAS unsigned char* lds, const Gemm g0, const StaticOrder& S, const Epi& E) {
;     ...
;             PG8_STAGE(PG8_SB(0, 1), b2 + hstep, voffB);
;             PG8_WAIT_V(6); PG8_BAR; PG8_MMA(1, 1, At, B1); PG8_BAR;
;             PG8_LDB(B0, 1, 0); PG8_SCHED; PG8_LDA(At, 1, 0); PG8_STAGE(PG8_SA(0, 1), a2 + hstep, voffA);
;             PG8_WAIT_L(8); PG8_BAR; PG8_WAIT_L(0); PG8_MMA(0, 0, At, B0); PG8_BAR; PG8_SCHED;
;             PG8_LDB(B1, 1, 1); PG8_STAGE(PG8_SB(1, 0), b3, voffB);
;             PG8_BAR; PG8_WAIT_L(0); PG8_MMA(0, 1, At, B1); PG8_BAR;
	s_add_u32 s12, s62, 0x160000
	s_addc_u32 s13, s63, 0
	s_add_i32 s23, s90, s19
	v_lshl_add_u64 v[130:131], s[12:13], 0, v[174:175]
	s_mov_b32 m0, s23
	s_nop 0
	global_load_lds_dwordx4 v[130:131], off
	v_lshl_add_u64 v[130:131], s[12:13], 0, v[158:159]
	s_add_i32 m0, s23, 0x2000
	s_nop 0
	global_load_lds_dwordx4 v[130:131], off
	s_waitcnt vmcnt(6)
	s_barrier
	s_setprio 0
	v_mfma_f32_16x16x32_f16 v[54:57], v[196:199], v[146:149], v[54:57]
	v_mfma_f32_16x16x32_f16 v[50:53], v[214:217], v[146:149], v[50:53]
	v_mfma_f32_16x16x32_f16 v[38:41], v[196:199], v[154:157], v[38:41]
	v_mfma_f32_16x16x32_f16 v[34:37], v[214:217], v[154:157], v[34:37]
	v_mfma_f32_16x16x32_f16 v[22:25], v[196:199], v[170:173], v[22:25]
	v_mfma_f32_16x16x32_f16 v[18:21], v[214:217], v[170:173], v[18:21]
	v_mfma_f32_16x16x32_f16 v[6:9], v[196:199], v[188:191], v[6:9]
	v_mfma_f32_16x16x32_f16 v[2:5], v[214:217], v[188:191], v[2:5]
	v_mfma_f32_16x16x32_f16 v[54:57], v[210:213], v[150:153], v[54:57]
	v_mfma_f32_16x16x32_f16 v[50:53], v[222:225], v[150:153], v[50:53]
	v_mfma_f32_16x16x32_f16 v[38:41], v[210:213], v[162:165], v[38:41]
	v_mfma_f32_16x16x32_f16 v[34:37], v[222:225], v[162:165], v[34:37]
	v_mfma_f32_16x16x32_f16 v[22:25], v[210:213], v[184:187], v[22:25]
	v_mfma_f32_16x16x32_f16 v[18:21], v[222:225], v[184:187], v[18:21]
	v_mfma_f32_16x16x32_f16 v[6:9], v[210:213], v[192:195], v[6:9]
	v_mfma_f32_16x16x32_f16 v[2:5], v[222:225], v[192:195], v[2:5]
	s_setprio 1
	s_add_i32 s23, 0, 0x18000
	v_add_u32_e32 v142, s23, v203
	s_barrier
	ds_read_b128 v[130:133], v142
	ds_read_b128 v[134:137], v142 offset:1024
	ds_read_b128 v[138:141], v142 offset:2048
	ds_read_b128 v[142:145], v142 offset:3072
	s_add_u32 s12, s80, 0x160000
	s_addc_u32 s13, s81, 0
	s_mov_b32 m0, s31
	v_lshl_add_u64 v[196:197], s[12:13], 0, v[176:177]
	ds_read_b128 v[146:149], v208 offset:32768
	ds_read_b128 v[150:153], v208 offset:33792
	ds_read_b128 v[154:157], v208 offset:34816
	ds_read_b128 v[162:165], v208 offset:35840
	ds_read_b128 v[170:173], v208 offset:36864
	ds_read_b128 v[184:187], v208 offset:37888
	ds_read_b128 v[188:191], v208 offset:38912
	ds_read_b128 v[192:195], v208 offset:39936
	global_load_lds_dwordx4 v[196:197], off
	v_lshl_add_u64 v[196:197], s[12:13], 0, v[160:161]
	s_mov_b32 m0, s61
	s_nop 0
	global_load_lds_dwordx4 v[196:197], off
	s_waitcnt lgkmcnt(8)
	s_barrier
	s_waitcnt lgkmcnt(0)
	s_setprio 0
	s_waitcnt lgkmcnt(0)
	v_mfma_f32_16x16x32_f16 v[126:129], v[130:133], v[146:149], v[126:129]
	v_mfma_f32_16x16x32_f16 v[122:125], v[138:141], v[146:149], v[122:125]
	v_mfma_f32_16x16x32_f16 v[110:113], v[130:133], v[154:157], v[110:113]
	v_mfma_f32_16x16x32_f16 v[106:109], v[138:141], v[154:157], v[106:109]
	v_mfma_f32_16x16x32_f16 v[94:97], v[130:133], v[170:173], v[94:97]
	v_mfma_f32_16x16x32_f16 v[90:93], v[138:141], v[170:173], v[90:93]
	v_mfma_f32_16x16x32_f16 v[78:81], v[130:133], v[188:191], v[78:81]
	v_mfma_f32_16x16x32_f16 v[74:77], v[138:141], v[188:191], v[74:77]
	v_mfma_f32_16x16x32_f16 v[126:129], v[134:137], v[150:153], v[126:129]
	v_mfma_f32_16x16x32_f16 v[122:125], v[142:145], v[150:153], v[122:125]
	v_mfma_f32_16x16x32_f16 v[110:113], v[134:137], v[162:165], v[110:113]
	v_mfma_f32_16x16x32_f16 v[106:109], v[142:145], v[162:165], v[106:109]
	v_mfma_f32_16x16x32_f16 v[94:97], v[134:137], v[184:187], v[94:97]
	v_mfma_f32_16x16x32_f16 v[90:93], v[142:145], v[184:187], v[90:93]
	v_mfma_f32_16x16x32_f16 v[78:81], v[134:137], v[192:195], v[78:81]
	v_mfma_f32_16x16x32_f16 v[74:77], v[142:145], v[192:195], v[74:77]
	s_setprio 1
	s_barrier
	s_add_i32 s80, 0, 0x1c000
	s_add_i32 s12, s23, s19
	v_add_u32_e32 v209, s80, v203
	v_lshl_add_u64 v[200:201], v[200:201], 0, s[64:65]
	s_mov_b32 m0, s12
	ds_read_b128 v[196:199], v209
	ds_read_b128 v[210:213], v209 offset:1024
	ds_read_b128 v[214:217], v209 offset:2048
	ds_read_b128 v[222:225], v209 offset:3072
	global_load_lds_dwordx4 v[200:201], off
	v_lshl_add_u64 v[200:201], v[218:219], 0, s[64:65]
	s_add_i32 m0, s12, 0x2000
	s_nop 0
	global_load_lds_dwordx4 v[200:201], off
	s_barrier
; #define GAS __attribute__((address_space(1)))
; #define PG8_STAGE(bufoff, gbase, voff) do { _Pragma("unroll") for (int _i = 0; _i < 2; ++_i) \
;         __builtin_amdgcn_global_load_lds((const unsigned*)((const char*)(gbase) + (voff)[_i]), (LAS unsigned*)(lds + (bufoff) + ldsw + _i * 8192), 16, 0, 0); } while (0)
; #define PG8_LDA(dst, b, h) do { _Pragma("unroll") for (int m = 0; m < 4; ++m) _Pragma("unroll") for (int k = 0; k < 2; ++k) dst[m][k] = *(const LAS f16x8*)(lds + PG8_SA(b, h) + aoff + m * 2048 + k * 1024); } while (0)
; #define PG8_MMA(ai, bj, At, Bt) do { __builtin_amdgcn_s_setprio(1); _Pragma("unroll") for (int m = 0; m < 4; ++m) _Pragma("unroll") for (int n = 0; n < 2; ++n) _Pragma("unroll") for (int k = 0; k < 2; ++k) \
;         acc[ai][bj][m][n] = __builtin_amdgcn_mfma_f32_16x16x32_f16(Bt[n][k], At[m][k], acc[ai][bj][m][n], 0, 0, 0); __builtin_amdgcn_s_setprio(0); } while (0)
; #define PG8_WAIT_V(n) asm volatile("s_waitcnt vmcnt(" #n ")" ::: "memory")
; #define PG8_WAIT_L(n) asm volatile("s_waitcnt lgkmcnt(" #n ")" ::: "memory")
; #define PG8_BAR __builtin_amdgcn_s_barrier()
; #define PG8_SCHED __builtin_amdgcn_sched_barrier(0)
;     __device__ __forceinline__ void operator()(f32x4 (&acc)[2][2][4][2], const Unit& u, int wr, int wc, int fr, int fq) const {
;     ...
;         { const int lane = fr + 16 * fq, cL = u.pn * BM + wc * 32 + (lane < 32 ? lane : 96 + lane);
;           float vg = 0.f, vb = 0.f, vt = 0.f;
;           if (hasln) { vg = *(const GAS float*)(pg + cL); vb = *(const GAS float*)(pb + cL); }
;           if (haszh) vt = *(const GAS float*)(tg + cL);
; template <class Epi>
; __device__ __forceinline__ void gemm_phase(LAS unsigned char* lds, const Gemm g0, const StaticOrder& S, const Epi& E) {
;     ...
;             PG8_LDA(At, 1, 1); PG8_STAGE(PG8_SA(1, 0), a3, voffA);
;             PG8_BAR; PG8_WAIT_L(0); PG8_MMA(1, 0, At, B0); PG8_BAR; PG8_SCHED;
;             PG8_STAGE(PG8_SB(1, 1), b3 + hstep, voffB);
;             PG8_WAIT_V(6); PG8_BAR; PG8_MMA(1, 1, At, B1); PG8_BAR;
;         }
	s_waitcnt lgkmcnt(0)
	s_setprio 0
	s_waitcnt lgkmcnt(0)
	v_mfma_f32_16x16x32_f16 v[118:121], v[196:199], v[146:149], v[118:121]
	v_mfma_f32_16x16x32_f16 v[114:117], v[214:217], v[146:149], v[114:117]
	v_mfma_f32_16x16x32_f16 v[102:105], v[196:199], v[154:157], v[102:105]
	v_mfma_f32_16x16x32_f16 v[98:101], v[214:217], v[154:157], v[98:101]
	v_mfma_f32_16x16x32_f16 v[86:89], v[196:199], v[170:173], v[86:89]
	v_mfma_f32_16x16x32_f16 v[82:85], v[214:217], v[170:173], v[82:85]
	v_mfma_f32_16x16x32_f16 v[70:73], v[196:199], v[188:191], v[70:73]
	v_mfma_f32_16x16x32_f16 v[66:69], v[214:217], v[188:191], v[66:69]
	v_mfma_f32_16x16x32_f16 v[118:121], v[210:213], v[150:153], v[118:121]
	v_mfma_f32_16x16x32_f16 v[114:117], v[222:225], v[150:153], v[114:117]
	v_mfma_f32_16x16x32_f16 v[102:105], v[210:213], v[162:165], v[102:105]
	v_mfma_f32_16x16x32_f16 v[98:101], v[222:225], v[162:165], v[98:101]
	v_mfma_f32_16x16x32_f16 v[86:89], v[210:213], v[184:187], v[86:89]
	v_mfma_f32_16x16x32_f16 v[82:85], v[222:225], v[184:187], v[82:85]
	v_mfma_f32_16x16x32_f16 v[70:73], v[210:213], v[192:195], v[70:73]
	v_mfma_f32_16x16x32_f16 v[66:69], v[222:225], v[192:195], v[66:69]
	s_setprio 1
	s_mov_b32 m0, s83
	v_lshl_add_u64 v[200:201], v[226:227], 0, s[64:65]
	s_barrier
	ds_read_b128 v[146:149], v208 offset:49152
	ds_read_b128 v[150:153], v208 offset:50176
	ds_read_b128 v[154:157], v208 offset:51200
	ds_read_b128 v[162:165], v208 offset:52224
	ds_read_b128 v[170:173], v208 offset:53248
	ds_read_b128 v[184:187], v208 offset:54272
	ds_read_b128 v[188:191], v208 offset:55296
	ds_read_b128 v[192:195], v208 offset:56320
	global_load_lds_dwordx4 v[200:201], off
	v_lshl_add_u64 v[200:201], v[228:229], 0, s[64:65]
	s_mov_b32 m0, s84
	s_nop 0
	global_load_lds_dwordx4 v[200:201], off
	s_barrier
	s_waitcnt lgkmcnt(0)
	s_setprio 0
	s_waitcnt lgkmcnt(0)
	v_mfma_f32_16x16x32_f16 v[62:65], v[130:133], v[146:149], v[62:65]
	v_mfma_f32_16x16x32_f16 v[58:61], v[138:141], v[146:149], v[58:61]
	v_mfma_f32_16x16x32_f16 v[46:49], v[130:133], v[154:157], v[46:49]
	v_mfma_f32_16x16x32_f16 v[42:45], v[138:141], v[154:157], v[42:45]
	v_mfma_f32_16x16x32_f16 v[30:33], v[130:133], v[170:173], v[30:33]
	v_mfma_f32_16x16x32_f16 v[26:29], v[138:141], v[170:173], v[26:29]
	v_mfma_f32_16x16x32_f16 v[14:17], v[130:133], v[188:191], v[14:17]
	v_mfma_f32_16x16x32_f16 v[10:13], v[138:141], v[188:191], v[10:13]
	v_mfma_f32_16x16x32_f16 v[62:65], v[134:137], v[150:153], v[62:65]
	v_mfma_f32_16x16x32_f16 v[58:61], v[142:145], v[150:153], v[58:61]
	v_mfma_f32_16x16x32_f16 v[46:49], v[134:137], v[162:165], v[46:49]
	v_mfma_f32_16x16x32_f16 v[42:45], v[142:145], v[162:165], v[42:45]
	v_mfma_f32_16x16x32_f16 v[30:33], v[134:137], v[184:187], v[30:33]
	v_mfma_f32_16x16x32_f16 v[26:29], v[142:145], v[184:187], v[26:29]
	v_mfma_f32_16x16x32_f16 v[14:17], v[134:137], v[192:195], v[14:17]
	v_mfma_f32_16x16x32_f16 v[10:13], v[142:145], v[192:195], v[10:13]
	s_setprio 1
	s_barrier
	s_add_u32 s12, s62, 0x160080
	s_addc_u32 s13, s63, 0
	s_add_i32 s23, s80, s19
	v_lshl_add_u64 v[130:131], s[12:13], 0, v[174:175]
	s_mov_b32 m0, s23
	s_nop 0
	global_load_lds_dwordx4 v[130:131], off
	v_lshl_add_u64 v[130:131], s[12:13], 0, v[158:159]
	s_add_i32 m0, s23, 0x2000
	s_nop 0
	global_load_lds_dwordx4 v[130:131], off
	s_waitcnt vmcnt(6)
	s_barrier
	s_setprio 0
	v_mfma_f32_16x16x32_f16 v[54:57], v[196:199], v[146:149], v[54:57]
	v_mfma_f32_16x16x32_f16 v[50:53], v[214:217], v[146:149], v[50:53]
	v_mfma_f32_16x16x32_f16 v[38:41], v[196:199], v[154:157], v[38:41]
	v_mfma_f32_16x16x32_f16 v[34:37], v[214:217], v[154:157], v[34:37]
	v_mfma_f32_16x16x32_f16 v[22:25], v[196:199], v[170:173], v[22:25]
	v_mfma_f32_16x16x32_f16 v[18:21], v[214:217], v[170:173], v[18:21]
	v_mfma_f32_16x16x32_f16 v[6:9], v[196:199], v[188:191], v[6:9]
	v_mfma_f32_16x16x32_f16 v[2:5], v[214:217], v[188:191], v[2:5]
	v_mfma_f32_16x16x32_f16 v[54:57], v[210:213], v[150:153], v[54:57]
	v_mfma_f32_16x16x32_f16 v[50:53], v[222:225], v[150:153], v[50:53]
	v_mfma_f32_16x16x32_f16 v[38:41], v[210:213], v[162:165], v[38:41]
	v_mfma_f32_16x16x32_f16 v[34:37], v[222:225], v[162:165], v[34:37]
	v_mfma_f32_16x16x32_f16 v[22:25], v[210:213], v[184:187], v[22:25]
	v_mfma_f32_16x16x32_f16 v[18:21], v[222:225], v[184:187], v[18:21]
	v_mfma_f32_16x16x32_f16 v[6:9], v[210:213], v[192:195], v[6:9]
	v_mfma_f32_16x16x32_f16 v[2:5], v[222:225], v[192:195], v[2:5]
	s_setprio 1
	s_add_i32 s22, s22, 2
	s_add_u32 s24, s24, 0x100
	s_addc_u32 s25, s25, 0
	s_cmpk_gt_u32 s22, 0x55
	s_mov_b64 s[12:13], s[10:11]
	s_barrier
	s_cbranch_scc0 .LBB0_672
	s_lshl_b32 s10, s92, 8
	s_or_b32 s12, s10, s82
	v_add_u32_e32 v130, s12, v204
	v_ashrrev_i32_e32 v131, 31, v130
	v_lshlrev_b64 v[132:133], 2, v[130:131]
	v_lshl_add_u64 v[134:135], s[38:39], 0, v[132:133]
	v_lshl_add_u64 v[132:133], s[48:49], 0, v[132:133]
	global_load_dword v146, v[134:135], off
	global_load_dword v147, v[132:133], off
	v_readlane_b32 s22, v254, 55
	v_readlane_b32 s23, v254, 56
	s_andn2_b64 vcc, exec, s[22:23]
	v_mov_b32_e32 v148, 0
	v_cndmask_b32_e64 v132, 0, 1, s[22:23]
	v_cmp_ne_u32_e64 s[10:11], 1, v132
	s_cbranch_vccnz .LBB0_675
	v_lshl_add_u64 v[130:131], v[130:131], 2, s[50:51]
	global_load_dword v148, v[130:131], off
